# merge: block behind the branch GEMM (sigmoid of the gate accumulators, gating, bf16 tile staging) hand-written; gate kept in f32 until the product
# speedup vs baseline: 1.1368x; 1.0058x over previous
; template <int NI, bool DEEP = true>
; DEV void gemm_tile(f32x16 (&acc)[2][NI], const bf16* __restrict__ A, int lda, const bf16* __restrict__ Bt, int ldb,
;                    int K, bf16* sA, bf16* sB) {
;     ...
;   G_LOAD(ra0, rb0, 0)
;   if (DEEP) {
;     if (64 < K) G_LOAD(ra1, rb1, 64)
;     for (int k0 = 0; k0 < K; k0 += 128) {
;       G_STEP(ra0, rb0, k0 + 128)
;       if (k0 + 64 < K) G_STEP(ra1, rb1, k0 + 192)
;     }
;   } else {
;     for (int k0 = 0; k0 < K; k0 += 64) G_STEP(ra0, rb0, k0 + 64)
;   }
; __device__ void phase_gemm1(PRef p, bf16* sA, bf16* sB) {
;     ...
;     gemm_tile<2>(acc, p.HY + (size_t)rt * 128 * 1024, 1024, p.WT1 + (size_t)ct * 128 * 1024, 1024, 1024, sA, sB);
.Lg1k_loop:
	s_waitcnt vmcnt(0)
	s_barrier
	ds_read_b128 v[88:91], v74 offset:0
	ds_read_b128 v[80:83], v70 offset:0
	ds_read_b128 v[84:87], v70 offset:4096
	ds_read_b128 v[92:95], v74 offset:4096
	s_waitcnt lgkmcnt(2)
	v_mfma_f32_32x32x16_bf16 v[52:67], v[88:91], v[80:83], v[52:67]
	s_add_u32 m0, s16, 0x8000
	s_nop 0
	global_load_lds_dwordx4 v68, s[98:99]
	ds_read_b128 v[104:107], v75 offset:0
	ds_read_b128 v[96:99], v71 offset:0
	s_waitcnt lgkmcnt(3)
	v_mfma_f32_32x32x16_bf16 v[20:35], v[88:91], v[84:87], v[20:35]
	s_add_u32 m0, s16, 0x8400
	s_add_u32 s14, s98, 0x4000
	s_addc_u32 s15, s99, 0
	global_load_lds_dwordx4 v69, s[14:15]
	ds_read_b128 v[100:103], v71 offset:4096
	s_waitcnt lgkmcnt(3)
	v_mfma_f32_32x32x16_bf16 v[36:51], v[92:95], v[80:83], v[36:51]
	s_add_u32 m0, s16, 0x8800
	s_add_u32 s14, s98, 0x8000
	s_addc_u32 s15, s99, 0
	global_load_lds_dwordx4 v68, s[14:15]
	ds_read_b128 v[108:111], v75 offset:4096
	v_mfma_f32_32x32x16_bf16 v[4:19], v[92:95], v[84:87], v[4:19]
	s_add_u32 m0, s16, 0x8c00
	s_add_u32 s14, s98, 0xc000
	s_addc_u32 s15, s99, 0
	global_load_lds_dwordx4 v69, s[14:15]
	s_waitcnt lgkmcnt(2)
	v_mfma_f32_32x32x16_bf16 v[52:67], v[104:107], v[96:99], v[52:67]
	s_add_u32 m0, s16, 0xd840
	s_nop 0
	global_load_lds_dwordx4 v68, s[100:101]
	ds_read_b128 v[120:123], v76 offset:0
	ds_read_b128 v[112:115], v72 offset:0
	s_waitcnt lgkmcnt(3)
	v_mfma_f32_32x32x16_bf16 v[20:35], v[104:107], v[100:103], v[20:35]
	s_add_u32 m0, s16, 0xdc40
	s_add_u32 s14, s100, 0x4000
	s_addc_u32 s15, s101, 0
	global_load_lds_dwordx4 v69, s[14:15]
	ds_read_b128 v[116:119], v72 offset:4096
	s_waitcnt lgkmcnt(3)
	v_mfma_f32_32x32x16_bf16 v[36:51], v[108:111], v[96:99], v[36:51]
	s_add_u32 m0, s16, 0xe040
	s_add_u32 s14, s100, 0x8000
	s_addc_u32 s15, s101, 0
	global_load_lds_dwordx4 v68, s[14:15]
	ds_read_b128 v[124:127], v76 offset:4096
	v_mfma_f32_32x32x16_bf16 v[4:19], v[108:111], v[100:103], v[4:19]
	s_add_u32 m0, s16, 0xe440
	s_add_u32 s14, s100, 0xc000
	s_addc_u32 s15, s101, 0
	global_load_lds_dwordx4 v69, s[14:15]
	s_waitcnt lgkmcnt(2)
	v_mfma_f32_32x32x16_bf16 v[52:67], v[120:123], v[112:115], v[52:67]
	s_add_u32 s98, s98, 0x80
	s_addc_u32 s99, s99, 0
	s_add_u32 s100, s100, 0x80
	s_addc_u32 s101, s101, 0
	ds_read_b128 v[88:91], v77 offset:0
	ds_read_b128 v[80:83], v73 offset:0
	s_waitcnt lgkmcnt(3)
	v_mfma_f32_32x32x16_bf16 v[20:35], v[120:123], v[116:119], v[20:35]
	ds_read_b128 v[84:87], v73 offset:4096
	s_waitcnt lgkmcnt(3)
	v_mfma_f32_32x32x16_bf16 v[36:51], v[124:127], v[112:115], v[36:51]
	ds_read_b128 v[92:95], v77 offset:4096
	v_mfma_f32_32x32x16_bf16 v[4:19], v[124:127], v[116:119], v[4:19]
	s_waitcnt lgkmcnt(2)
	v_mfma_f32_32x32x16_bf16 v[52:67], v[88:91], v[80:83], v[52:67]
	s_waitcnt lgkmcnt(1)
	v_mfma_f32_32x32x16_bf16 v[20:35], v[88:91], v[84:87], v[20:35]
	s_waitcnt lgkmcnt(0)
	v_mfma_f32_32x32x16_bf16 v[36:51], v[92:95], v[80:83], v[36:51]
	v_mfma_f32_32x32x16_bf16 v[4:19], v[92:95], v[84:87], v[4:19]
	s_waitcnt vmcnt(0)
	s_barrier
	s_cmp_eq_u32 s11, 7
	s_cbranch_scc1 .Lg1k_nodma
	ds_read_b128 v[88:91], v74 offset:38976
	ds_read_b128 v[80:83], v70 offset:32768
	ds_read_b128 v[84:87], v70 offset:36864
	ds_read_b128 v[92:95], v74 offset:43072
	s_waitcnt lgkmcnt(2)
	v_mfma_f32_32x32x16_bf16 v[52:67], v[88:91], v[80:83], v[52:67]
	s_add_u32 m0, s16, 0x0
	s_nop 0
	global_load_lds_dwordx4 v68, s[98:99]
	ds_read_b128 v[104:107], v75 offset:38976
	ds_read_b128 v[96:99], v71 offset:32768
	s_waitcnt lgkmcnt(3)
	v_mfma_f32_32x32x16_bf16 v[20:35], v[88:91], v[84:87], v[20:35]
	s_add_u32 m0, s16, 0x400
	s_add_u32 s14, s98, 0x4000
	s_addc_u32 s15, s99, 0
	global_load_lds_dwordx4 v69, s[14:15]
	ds_read_b128 v[100:103], v71 offset:36864
	s_waitcnt lgkmcnt(3)
	v_mfma_f32_32x32x16_bf16 v[36:51], v[92:95], v[80:83], v[36:51]
	s_add_u32 m0, s16, 0x800
	s_add_u32 s14, s98, 0x8000
	s_addc_u32 s15, s99, 0
	global_load_lds_dwordx4 v68, s[14:15]
	ds_read_b128 v[108:111], v75 offset:43072
	v_mfma_f32_32x32x16_bf16 v[4:19], v[92:95], v[84:87], v[4:19]
	s_add_u32 m0, s16, 0xc00
	s_add_u32 s14, s98, 0xc000
	s_addc_u32 s15, s99, 0
	global_load_lds_dwordx4 v69, s[14:15]
	s_waitcnt lgkmcnt(2)
	v_mfma_f32_32x32x16_bf16 v[52:67], v[104:107], v[96:99], v[52:67]
	s_add_u32 m0, s16, 0x4000
	s_nop 0
	global_load_lds_dwordx4 v68, s[100:101]
	ds_read_b128 v[120:123], v76 offset:38976
	ds_read_b128 v[112:115], v72 offset:32768
	s_waitcnt lgkmcnt(3)
	v_mfma_f32_32x32x16_bf16 v[20:35], v[104:107], v[100:103], v[20:35]
	s_add_u32 m0, s16, 0x4400
	s_add_u32 s14, s100, 0x4000
	s_addc_u32 s15, s101, 0
	global_load_lds_dwordx4 v69, s[14:15]
	ds_read_b128 v[116:119], v72 offset:36864
	s_waitcnt lgkmcnt(3)
	v_mfma_f32_32x32x16_bf16 v[36:51], v[108:111], v[96:99], v[36:51]
	s_add_u32 m0, s16, 0x4800
	s_add_u32 s14, s100, 0x8000
	s_addc_u32 s15, s101, 0
	global_load_lds_dwordx4 v68, s[14:15]
	ds_read_b128 v[124:127], v76 offset:43072
	v_mfma_f32_32x32x16_bf16 v[4:19], v[108:111], v[100:103], v[4:19]
	s_add_u32 m0, s16, 0x4c00
	s_add_u32 s14, s100, 0xc000
	s_addc_u32 s15, s101, 0
	global_load_lds_dwordx4 v69, s[14:15]
	s_waitcnt lgkmcnt(2)
	v_mfma_f32_32x32x16_bf16 v[52:67], v[120:123], v[112:115], v[52:67]
	s_add_u32 s98, s98, 0x80
	s_addc_u32 s99, s99, 0
	s_add_u32 s100, s100, 0x80
	s_addc_u32 s101, s101, 0
	ds_read_b128 v[88:91], v77 offset:38976
	ds_read_b128 v[80:83], v73 offset:32768
	s_waitcnt lgkmcnt(3)
	v_mfma_f32_32x32x16_bf16 v[20:35], v[120:123], v[116:119], v[20:35]
	ds_read_b128 v[84:87], v73 offset:36864
	s_waitcnt lgkmcnt(3)
	v_mfma_f32_32x32x16_bf16 v[36:51], v[124:127], v[112:115], v[36:51]
	ds_read_b128 v[92:95], v77 offset:43072
	v_mfma_f32_32x32x16_bf16 v[4:19], v[124:127], v[116:119], v[4:19]
	s_waitcnt lgkmcnt(2)
	v_mfma_f32_32x32x16_bf16 v[52:67], v[88:91], v[80:83], v[52:67]
	s_waitcnt lgkmcnt(1)
	v_mfma_f32_32x32x16_bf16 v[20:35], v[88:91], v[84:87], v[20:35]
	s_waitcnt lgkmcnt(0)
	v_mfma_f32_32x32x16_bf16 v[36:51], v[92:95], v[80:83], v[36:51]
	v_mfma_f32_32x32x16_bf16 v[4:19], v[92:95], v[84:87], v[4:19]
	s_branch .Lg1k_next
; template <int NI, bool DEEP = true>
; DEV void gemm_tile(f32x16 (&acc)[2][NI], const bf16* __restrict__ A, int lda, const bf16* __restrict__ Bt, int ldb,
;                    int K, bf16* sA, bf16* sB) {
;     ...
;     for (int k0 = 0; k0 < K; k0 += 64) G_STEP(ra0, rb0, k0 + 64)
.Lg1k_nodma:
	ds_read_b128 v[88:91], v74 offset:38976
	ds_read_b128 v[80:83], v70 offset:32768
	ds_read_b128 v[84:87], v70 offset:36864
	ds_read_b128 v[92:95], v74 offset:43072
	s_waitcnt lgkmcnt(2)
	v_mfma_f32_32x32x16_bf16 v[52:67], v[88:91], v[80:83], v[52:67]
	ds_read_b128 v[104:107], v75 offset:38976
	ds_read_b128 v[96:99], v71 offset:32768
	s_waitcnt lgkmcnt(3)
	v_mfma_f32_32x32x16_bf16 v[20:35], v[88:91], v[84:87], v[20:35]
	ds_read_b128 v[100:103], v71 offset:36864
	s_waitcnt lgkmcnt(3)
	v_mfma_f32_32x32x16_bf16 v[36:51], v[92:95], v[80:83], v[36:51]
	ds_read_b128 v[108:111], v75 offset:43072
	v_mfma_f32_32x32x16_bf16 v[4:19], v[92:95], v[84:87], v[4:19]
	s_waitcnt lgkmcnt(2)
	v_mfma_f32_32x32x16_bf16 v[52:67], v[104:107], v[96:99], v[52:67]
	ds_read_b128 v[120:123], v76 offset:38976
	ds_read_b128 v[112:115], v72 offset:32768
	s_waitcnt lgkmcnt(3)
	v_mfma_f32_32x32x16_bf16 v[20:35], v[104:107], v[100:103], v[20:35]
	ds_read_b128 v[116:119], v72 offset:36864
	s_waitcnt lgkmcnt(3)
	v_mfma_f32_32x32x16_bf16 v[36:51], v[108:111], v[96:99], v[36:51]
	ds_read_b128 v[124:127], v76 offset:43072
	v_mfma_f32_32x32x16_bf16 v[4:19], v[108:111], v[100:103], v[4:19]
	s_waitcnt lgkmcnt(2)
	v_mfma_f32_32x32x16_bf16 v[52:67], v[120:123], v[112:115], v[52:67]
	ds_read_b128 v[88:91], v77 offset:38976
	ds_read_b128 v[80:83], v73 offset:32768
	s_waitcnt lgkmcnt(3)
	v_mfma_f32_32x32x16_bf16 v[20:35], v[120:123], v[116:119], v[20:35]
	ds_read_b128 v[84:87], v73 offset:36864
	s_waitcnt lgkmcnt(3)
	v_mfma_f32_32x32x16_bf16 v[36:51], v[124:127], v[112:115], v[36:51]
	ds_read_b128 v[92:95], v77 offset:43072
	v_mfma_f32_32x32x16_bf16 v[4:19], v[124:127], v[116:119], v[4:19]
	s_waitcnt lgkmcnt(2)
	v_mfma_f32_32x32x16_bf16 v[52:67], v[88:91], v[80:83], v[52:67]
	s_waitcnt lgkmcnt(1)
	v_mfma_f32_32x32x16_bf16 v[20:35], v[88:91], v[84:87], v[20:35]
	s_waitcnt lgkmcnt(0)
	v_mfma_f32_32x32x16_bf16 v[36:51], v[92:95], v[80:83], v[36:51]
	v_mfma_f32_32x32x16_bf16 v[4:19], v[92:95], v[84:87], v[4:19]

; template <int NI, bool DEEP = true>
; DEV void gemm_tile(f32x16 (&acc)[2][NI], const bf16* __restrict__ A, int lda, const bf16* __restrict__ Bt, int ldb,
;                    int K, bf16* sA, bf16* sB) {
;     ...
;   G_LOAD(ra0, rb0, 0)
;   if (DEEP) {
;     if (64 < K) G_LOAD(ra1, rb1, 64)
;     for (int k0 = 0; k0 < K; k0 += 128) {
;       G_STEP(ra0, rb0, k0 + 128)
;       if (k0 + 64 < K) G_STEP(ra1, rb1, k0 + 192)
;     }
;   } else {
;     for (int k0 = 0; k0 < K; k0 += 64) G_STEP(ra0, rb0, k0 + 64)
;   }
; __device__ void phase_gates(PRef p, int l, const bf16* H2, bf16* sA, bf16* sB) {
;     ...
;     gemm_tile<2>(acc, H2 + (size_t)rt * 128 * 1024, 1024, p.WT2 + (size_t)ct * 128 * 1024, 1024, 1024, sA, sB);
.Lgtk_loop:
	s_waitcnt vmcnt(0)
	s_barrier
	ds_read_b128 v[88:91], v74 offset:0
	ds_read_b128 v[80:83], v70 offset:0
	ds_read_b128 v[84:87], v70 offset:4096
	ds_read_b128 v[92:95], v74 offset:4096
	s_waitcnt lgkmcnt(2)
	v_mfma_f32_32x32x16_bf16 v[52:67], v[88:91], v[80:83], v[52:67]
	s_add_u32 m0, s0, 0x8000
	s_nop 0
	global_load_lds_dwordx4 v68, s[98:99]
	ds_read_b128 v[104:107], v75 offset:0
	ds_read_b128 v[96:99], v71 offset:0
	s_waitcnt lgkmcnt(3)
	v_mfma_f32_32x32x16_bf16 v[20:35], v[88:91], v[84:87], v[20:35]
	s_add_u32 m0, s0, 0x8400
	s_add_u32 s14, s98, 0x4000
	s_addc_u32 s15, s99, 0
	global_load_lds_dwordx4 v69, s[14:15]
	ds_read_b128 v[100:103], v71 offset:4096
	s_waitcnt lgkmcnt(3)
	v_mfma_f32_32x32x16_bf16 v[36:51], v[92:95], v[80:83], v[36:51]
	s_add_u32 m0, s0, 0x8800
	s_add_u32 s14, s98, 0x8000
	s_addc_u32 s15, s99, 0
	global_load_lds_dwordx4 v68, s[14:15]
	ds_read_b128 v[108:111], v75 offset:4096
	v_mfma_f32_32x32x16_bf16 v[4:19], v[92:95], v[84:87], v[4:19]
	s_add_u32 m0, s0, 0x8c00
	s_add_u32 s14, s98, 0xc000
	s_addc_u32 s15, s99, 0
	global_load_lds_dwordx4 v69, s[14:15]
	s_waitcnt lgkmcnt(2)
	v_mfma_f32_32x32x16_bf16 v[52:67], v[104:107], v[96:99], v[52:67]
	s_add_u32 m0, s0, 0xd840
	s_nop 0
	global_load_lds_dwordx4 v68, s[100:101]
	ds_read_b128 v[120:123], v76 offset:0
	ds_read_b128 v[112:115], v72 offset:0
	s_waitcnt lgkmcnt(3)
	v_mfma_f32_32x32x16_bf16 v[20:35], v[104:107], v[100:103], v[20:35]
	s_add_u32 m0, s0, 0xdc40
	s_add_u32 s14, s100, 0x4000
	s_addc_u32 s15, s101, 0
	global_load_lds_dwordx4 v69, s[14:15]
	ds_read_b128 v[116:119], v72 offset:4096
	s_waitcnt lgkmcnt(3)
	v_mfma_f32_32x32x16_bf16 v[36:51], v[108:111], v[96:99], v[36:51]
	s_add_u32 m0, s0, 0xe040
	s_add_u32 s14, s100, 0x8000
	s_addc_u32 s15, s101, 0
	global_load_lds_dwordx4 v68, s[14:15]
	ds_read_b128 v[124:127], v76 offset:4096
	v_mfma_f32_32x32x16_bf16 v[4:19], v[108:111], v[100:103], v[4:19]
	s_add_u32 m0, s0, 0xe440
	s_add_u32 s14, s100, 0xc000
	s_addc_u32 s15, s101, 0
	global_load_lds_dwordx4 v69, s[14:15]
	s_waitcnt lgkmcnt(2)
	v_mfma_f32_32x32x16_bf16 v[52:67], v[120:123], v[112:115], v[52:67]
	s_add_u32 s98, s98, 0x80
	s_addc_u32 s99, s99, 0
	s_add_u32 s100, s100, 0x80
	s_addc_u32 s101, s101, 0
	ds_read_b128 v[88:91], v77 offset:0
	ds_read_b128 v[80:83], v73 offset:0
	s_waitcnt lgkmcnt(3)
	v_mfma_f32_32x32x16_bf16 v[20:35], v[120:123], v[116:119], v[20:35]
	ds_read_b128 v[84:87], v73 offset:4096
	s_waitcnt lgkmcnt(3)
	v_mfma_f32_32x32x16_bf16 v[36:51], v[124:127], v[112:115], v[36:51]
	ds_read_b128 v[92:95], v77 offset:4096
	v_mfma_f32_32x32x16_bf16 v[4:19], v[124:127], v[116:119], v[4:19]
	s_waitcnt lgkmcnt(2)
	v_mfma_f32_32x32x16_bf16 v[52:67], v[88:91], v[80:83], v[52:67]
	s_waitcnt lgkmcnt(1)
	v_mfma_f32_32x32x16_bf16 v[20:35], v[88:91], v[84:87], v[20:35]
	s_waitcnt lgkmcnt(0)
	v_mfma_f32_32x32x16_bf16 v[36:51], v[92:95], v[80:83], v[36:51]
	v_mfma_f32_32x32x16_bf16 v[4:19], v[92:95], v[84:87], v[4:19]
	s_waitcnt vmcnt(0)
	s_barrier
	s_cmp_eq_u32 s11, 7
	s_cbranch_scc1 .Lgtk_nodma
	ds_read_b128 v[88:91], v74 offset:38976
	ds_read_b128 v[80:83], v70 offset:32768
	ds_read_b128 v[84:87], v70 offset:36864
	ds_read_b128 v[92:95], v74 offset:43072
	s_waitcnt lgkmcnt(2)
	v_mfma_f32_32x32x16_bf16 v[52:67], v[88:91], v[80:83], v[52:67]
	s_add_u32 m0, s0, 0x0
	s_nop 0
	global_load_lds_dwordx4 v68, s[98:99]
	ds_read_b128 v[104:107], v75 offset:38976
	ds_read_b128 v[96:99], v71 offset:32768
	s_waitcnt lgkmcnt(3)
	v_mfma_f32_32x32x16_bf16 v[20:35], v[88:91], v[84:87], v[20:35]
	s_add_u32 m0, s0, 0x400
	s_add_u32 s14, s98, 0x4000
	s_addc_u32 s15, s99, 0
	global_load_lds_dwordx4 v69, s[14:15]
	ds_read_b128 v[100:103], v71 offset:36864
	s_waitcnt lgkmcnt(3)
	v_mfma_f32_32x32x16_bf16 v[36:51], v[92:95], v[80:83], v[36:51]
	s_add_u32 m0, s0, 0x800
	s_add_u32 s14, s98, 0x8000
	s_addc_u32 s15, s99, 0
	global_load_lds_dwordx4 v68, s[14:15]
	ds_read_b128 v[108:111], v75 offset:43072
	v_mfma_f32_32x32x16_bf16 v[4:19], v[92:95], v[84:87], v[4:19]
	s_add_u32 m0, s0, 0xc00
	s_add_u32 s14, s98, 0xc000
	s_addc_u32 s15, s99, 0
	global_load_lds_dwordx4 v69, s[14:15]
	s_waitcnt lgkmcnt(2)
	v_mfma_f32_32x32x16_bf16 v[52:67], v[104:107], v[96:99], v[52:67]
	s_add_u32 m0, s0, 0x4000
	s_nop 0
	global_load_lds_dwordx4 v68, s[100:101]
	ds_read_b128 v[120:123], v76 offset:38976
	ds_read_b128 v[112:115], v72 offset:32768
	s_waitcnt lgkmcnt(3)
	v_mfma_f32_32x32x16_bf16 v[20:35], v[104:107], v[100:103], v[20:35]
	s_add_u32 m0, s0, 0x4400
	s_add_u32 s14, s100, 0x4000
	s_addc_u32 s15, s101, 0
	global_load_lds_dwordx4 v69, s[14:15]
	ds_read_b128 v[116:119], v72 offset:36864
	s_waitcnt lgkmcnt(3)
	v_mfma_f32_32x32x16_bf16 v[36:51], v[108:111], v[96:99], v[36:51]
	s_add_u32 m0, s0, 0x4800
	s_add_u32 s14, s100, 0x8000
	s_addc_u32 s15, s101, 0
	global_load_lds_dwordx4 v68, s[14:15]
	ds_read_b128 v[124:127], v76 offset:43072
	v_mfma_f32_32x32x16_bf16 v[4:19], v[108:111], v[100:103], v[4:19]
	s_add_u32 m0, s0, 0x4c00
	s_add_u32 s14, s100, 0xc000
	s_addc_u32 s15, s101, 0
	global_load_lds_dwordx4 v69, s[14:15]
	s_waitcnt lgkmcnt(2)
	v_mfma_f32_32x32x16_bf16 v[52:67], v[120:123], v[112:115], v[52:67]
	s_add_u32 s98, s98, 0x80
	s_addc_u32 s99, s99, 0
	s_add_u32 s100, s100, 0x80
	s_addc_u32 s101, s101, 0
	ds_read_b128 v[88:91], v77 offset:38976
	ds_read_b128 v[80:83], v73 offset:32768
	s_waitcnt lgkmcnt(3)
	v_mfma_f32_32x32x16_bf16 v[20:35], v[120:123], v[116:119], v[20:35]
	ds_read_b128 v[84:87], v73 offset:36864
	s_waitcnt lgkmcnt(3)
	v_mfma_f32_32x32x16_bf16 v[36:51], v[124:127], v[112:115], v[36:51]
	ds_read_b128 v[92:95], v77 offset:43072
	v_mfma_f32_32x32x16_bf16 v[4:19], v[124:127], v[116:119], v[4:19]
	s_waitcnt lgkmcnt(2)
	v_mfma_f32_32x32x16_bf16 v[52:67], v[88:91], v[80:83], v[52:67]
	s_waitcnt lgkmcnt(1)
	v_mfma_f32_32x32x16_bf16 v[20:35], v[88:91], v[84:87], v[20:35]
	s_waitcnt lgkmcnt(0)
	v_mfma_f32_32x32x16_bf16 v[36:51], v[92:95], v[80:83], v[36:51]
	v_mfma_f32_32x32x16_bf16 v[4:19], v[92:95], v[84:87], v[4:19]
	s_branch .Lgtk_next

; template <int NI, bool DEEP = true>
; DEV void gemm_tile(f32x16 (&acc)[2][NI], const bf16* __restrict__ A, int lda, const bf16* __restrict__ Bt, int ldb,
;                    int K, bf16* sA, bf16* sB) {
;     ...
;   G_LOAD(ra0, rb0, 0)
;   if (DEEP) {
;     if (64 < K) G_LOAD(ra1, rb1, 64)
;     for (int k0 = 0; k0 < K; k0 += 128) {
;       G_STEP(ra0, rb0, k0 + 128)
;       if (k0 + 64 < K) G_STEP(ra1, rb1, k0 + 192)
;     }
;   } else {
;     for (int k0 = 0; k0 < K; k0 += 64) G_STEP(ra0, rb0, k0 + 64)
;   }
; __device__ void phase_merge(PRef p, int l, const bf16* H2, bf16* M, bf16* sA, bf16* sB) {
;     ...
;         gemm_tile<2>(a2, H2 + (size_t)rt * 128 * 1024, 1024, p.WT3 + ((size_t)n * 1024 + ct * 128) * 1024, 1024, 1024, sA, sB);
.Lmak_loop:
	s_waitcnt vmcnt(0)
	s_barrier
	ds_read_b128 v[40:43], v26 offset:0
	ds_read_b128 v[32:35], v22 offset:0
	ds_read_b128 v[36:39], v22 offset:4096
	ds_read_b128 v[44:47], v26 offset:4096
	s_waitcnt lgkmcnt(2)
	v_mfma_f32_32x32x16_bf16 v[116:131], v[40:43], v[32:35], v[116:131]
	s_add_u32 m0, s0, 0x8000
	s_nop 0
	global_load_lds_dwordx4 v20, s[98:99]
	ds_read_b128 v[56:59], v27 offset:0
	ds_read_b128 v[48:51], v23 offset:0
	s_waitcnt lgkmcnt(3)
	v_mfma_f32_32x32x16_bf16 v[68:83], v[40:43], v[36:39], v[68:83]
	s_add_u32 m0, s0, 0x8400
	s_add_u32 s34, s98, 0x4000
	s_addc_u32 s35, s99, 0
	global_load_lds_dwordx4 v21, s[34:35]
	ds_read_b128 v[52:55], v23 offset:4096
	s_waitcnt lgkmcnt(3)
	v_mfma_f32_32x32x16_bf16 v[100:115], v[44:47], v[32:35], v[100:115]
	s_add_u32 m0, s0, 0x8800
	s_add_u32 s34, s98, 0x8000
	s_addc_u32 s35, s99, 0
	global_load_lds_dwordx4 v20, s[34:35]
	ds_read_b128 v[60:63], v27 offset:4096
	v_mfma_f32_32x32x16_bf16 v[4:19], v[44:47], v[36:39], v[4:19]
	s_add_u32 m0, s0, 0x8c00
	s_add_u32 s34, s98, 0xc000
	s_addc_u32 s35, s99, 0
	global_load_lds_dwordx4 v21, s[34:35]
	s_waitcnt lgkmcnt(2)
	v_mfma_f32_32x32x16_bf16 v[116:131], v[56:59], v[48:51], v[116:131]
	s_add_u32 m0, s0, 0xd840
	s_nop 0
	global_load_lds_dwordx4 v20, s[100:101]
	ds_read_b128 v[92:95], v28 offset:0
	ds_read_b128 v[84:87], v24 offset:0
	s_waitcnt lgkmcnt(3)
	v_mfma_f32_32x32x16_bf16 v[68:83], v[56:59], v[52:55], v[68:83]
	s_add_u32 m0, s0, 0xdc40
	s_add_u32 s34, s100, 0x4000
	s_addc_u32 s35, s101, 0
	global_load_lds_dwordx4 v21, s[34:35]
	ds_read_b128 v[88:91], v24 offset:4096
	s_waitcnt lgkmcnt(3)
	v_mfma_f32_32x32x16_bf16 v[100:115], v[60:63], v[48:51], v[100:115]
	s_add_u32 m0, s0, 0xe040
	s_add_u32 s34, s100, 0x8000
	s_addc_u32 s35, s101, 0
	global_load_lds_dwordx4 v20, s[34:35]
	ds_read_b128 v[96:99], v28 offset:4096
	v_mfma_f32_32x32x16_bf16 v[4:19], v[60:63], v[52:55], v[4:19]
	s_add_u32 m0, s0, 0xe440
	s_add_u32 s34, s100, 0xc000
	s_addc_u32 s35, s101, 0
	global_load_lds_dwordx4 v21, s[34:35]
	s_waitcnt lgkmcnt(2)
	v_mfma_f32_32x32x16_bf16 v[116:131], v[92:95], v[84:87], v[116:131]
	s_add_u32 s98, s98, 0x80
	s_addc_u32 s99, s99, 0
	s_add_u32 s100, s100, 0x80
	s_addc_u32 s101, s101, 0
	ds_read_b128 v[40:43], v29 offset:0
	ds_read_b128 v[32:35], v25 offset:0
	s_waitcnt lgkmcnt(3)
	v_mfma_f32_32x32x16_bf16 v[68:83], v[92:95], v[88:91], v[68:83]
	ds_read_b128 v[36:39], v25 offset:4096
	s_waitcnt lgkmcnt(3)
	v_mfma_f32_32x32x16_bf16 v[100:115], v[96:99], v[84:87], v[100:115]
	ds_read_b128 v[44:47], v29 offset:4096
	v_mfma_f32_32x32x16_bf16 v[4:19], v[96:99], v[88:91], v[4:19]
	s_waitcnt lgkmcnt(2)
	v_mfma_f32_32x32x16_bf16 v[116:131], v[40:43], v[32:35], v[116:131]
	s_waitcnt lgkmcnt(1)
	v_mfma_f32_32x32x16_bf16 v[68:83], v[40:43], v[36:39], v[68:83]
	s_waitcnt lgkmcnt(0)
	v_mfma_f32_32x32x16_bf16 v[100:115], v[44:47], v[32:35], v[100:115]
	v_mfma_f32_32x32x16_bf16 v[4:19], v[44:47], v[36:39], v[4:19]
	s_waitcnt vmcnt(0)
	s_barrier
	s_cmp_eq_u32 s28, 7
	s_cbranch_scc1 .Lmak_nodma
	ds_read_b128 v[40:43], v26 offset:38976
	ds_read_b128 v[32:35], v22 offset:32768
	ds_read_b128 v[36:39], v22 offset:36864
	ds_read_b128 v[44:47], v26 offset:43072
	s_waitcnt lgkmcnt(2)
	v_mfma_f32_32x32x16_bf16 v[116:131], v[40:43], v[32:35], v[116:131]
	s_add_u32 m0, s0, 0x0
	s_nop 0
	global_load_lds_dwordx4 v20, s[98:99]
	ds_read_b128 v[56:59], v27 offset:38976
	ds_read_b128 v[48:51], v23 offset:32768
	s_waitcnt lgkmcnt(3)
	v_mfma_f32_32x32x16_bf16 v[68:83], v[40:43], v[36:39], v[68:83]
	s_add_u32 m0, s0, 0x400
	s_add_u32 s34, s98, 0x4000
	s_addc_u32 s35, s99, 0
	global_load_lds_dwordx4 v21, s[34:35]
	ds_read_b128 v[52:55], v23 offset:36864
	s_waitcnt lgkmcnt(3)
	v_mfma_f32_32x32x16_bf16 v[100:115], v[44:47], v[32:35], v[100:115]
	s_add_u32 m0, s0, 0x800
	s_add_u32 s34, s98, 0x8000
	s_addc_u32 s35, s99, 0
	global_load_lds_dwordx4 v20, s[34:35]
	ds_read_b128 v[60:63], v27 offset:43072
	v_mfma_f32_32x32x16_bf16 v[4:19], v[44:47], v[36:39], v[4:19]
	s_add_u32 m0, s0, 0xc00
	s_add_u32 s34, s98, 0xc000
	s_addc_u32 s35, s99, 0
	global_load_lds_dwordx4 v21, s[34:35]
	s_waitcnt lgkmcnt(2)
	v_mfma_f32_32x32x16_bf16 v[116:131], v[56:59], v[48:51], v[116:131]
	s_add_u32 m0, s0, 0x4000
	s_nop 0
	global_load_lds_dwordx4 v20, s[100:101]
	ds_read_b128 v[92:95], v28 offset:38976
	ds_read_b128 v[84:87], v24 offset:32768
	s_waitcnt lgkmcnt(3)
	v_mfma_f32_32x32x16_bf16 v[68:83], v[56:59], v[52:55], v[68:83]
	s_add_u32 m0, s0, 0x4400
	s_add_u32 s34, s100, 0x4000
	s_addc_u32 s35, s101, 0
	global_load_lds_dwordx4 v21, s[34:35]
	ds_read_b128 v[88:91], v24 offset:36864
	s_waitcnt lgkmcnt(3)
	v_mfma_f32_32x32x16_bf16 v[100:115], v[60:63], v[48:51], v[100:115]
	s_add_u32 m0, s0, 0x4800
	s_add_u32 s34, s100, 0x8000
	s_addc_u32 s35, s101, 0
	global_load_lds_dwordx4 v20, s[34:35]
	ds_read_b128 v[96:99], v28 offset:43072
	v_mfma_f32_32x32x16_bf16 v[4:19], v[60:63], v[52:55], v[4:19]
	s_add_u32 m0, s0, 0x4c00
	s_add_u32 s34, s100, 0xc000
	s_addc_u32 s35, s101, 0
	global_load_lds_dwordx4 v21, s[34:35]
	s_waitcnt lgkmcnt(2)
	v_mfma_f32_32x32x16_bf16 v[116:131], v[92:95], v[84:87], v[116:131]
	s_add_u32 s98, s98, 0x80
	s_addc_u32 s99, s99, 0
	s_add_u32 s100, s100, 0x80
	s_addc_u32 s101, s101, 0
	ds_read_b128 v[40:43], v29 offset:38976
	ds_read_b128 v[32:35], v25 offset:32768
	s_waitcnt lgkmcnt(3)
	v_mfma_f32_32x32x16_bf16 v[68:83], v[92:95], v[88:91], v[68:83]
	ds_read_b128 v[36:39], v25 offset:36864
	s_waitcnt lgkmcnt(3)
	v_mfma_f32_32x32x16_bf16 v[100:115], v[96:99], v[84:87], v[100:115]
	ds_read_b128 v[44:47], v29 offset:43072
	v_mfma_f32_32x32x16_bf16 v[4:19], v[96:99], v[88:91], v[4:19]
	s_waitcnt lgkmcnt(2)
	v_mfma_f32_32x32x16_bf16 v[116:131], v[40:43], v[32:35], v[116:131]
	s_waitcnt lgkmcnt(1)
	v_mfma_f32_32x32x16_bf16 v[68:83], v[40:43], v[36:39], v[68:83]
	s_waitcnt lgkmcnt(0)
	v_mfma_f32_32x32x16_bf16 v[100:115], v[44:47], v[32:35], v[100:115]
	v_mfma_f32_32x32x16_bf16 v[4:19], v[44:47], v[36:39], v[4:19]
	s_branch .Lmak_next
; template <int NI, bool DEEP = true>
; DEV void gemm_tile(f32x16 (&acc)[2][NI], const bf16* __restrict__ A, int lda, const bf16* __restrict__ Bt, int ldb,
;                    int K, bf16* sA, bf16* sB) {
;     ...
;     for (int k0 = 0; k0 < K; k0 += 64) G_STEP(ra0, rb0, k0 + 64)
.Lmak_nodma:
	ds_read_b128 v[40:43], v26 offset:38976
	ds_read_b128 v[32:35], v22 offset:32768
	ds_read_b128 v[36:39], v22 offset:36864
	ds_read_b128 v[44:47], v26 offset:43072
	s_waitcnt lgkmcnt(2)
	v_mfma_f32_32x32x16_bf16 v[116:131], v[40:43], v[32:35], v[116:131]
	ds_read_b128 v[56:59], v27 offset:38976
	ds_read_b128 v[48:51], v23 offset:32768
	s_waitcnt lgkmcnt(3)
	v_mfma_f32_32x32x16_bf16 v[68:83], v[40:43], v[36:39], v[68:83]
	ds_read_b128 v[52:55], v23 offset:36864
	s_waitcnt lgkmcnt(3)
	v_mfma_f32_32x32x16_bf16 v[100:115], v[44:47], v[32:35], v[100:115]
	ds_read_b128 v[60:63], v27 offset:43072
	v_mfma_f32_32x32x16_bf16 v[4:19], v[44:47], v[36:39], v[4:19]
	s_waitcnt lgkmcnt(2)
	v_mfma_f32_32x32x16_bf16 v[116:131], v[56:59], v[48:51], v[116:131]
	ds_read_b128 v[92:95], v28 offset:38976
	ds_read_b128 v[84:87], v24 offset:32768
	s_waitcnt lgkmcnt(3)
	v_mfma_f32_32x32x16_bf16 v[68:83], v[56:59], v[52:55], v[68:83]
	ds_read_b128 v[88:91], v24 offset:36864
	s_waitcnt lgkmcnt(3)
	v_mfma_f32_32x32x16_bf16 v[100:115], v[60:63], v[48:51], v[100:115]
	ds_read_b128 v[96:99], v28 offset:43072
	v_mfma_f32_32x32x16_bf16 v[4:19], v[60:63], v[52:55], v[4:19]
	s_waitcnt lgkmcnt(2)
	v_mfma_f32_32x32x16_bf16 v[116:131], v[92:95], v[84:87], v[116:131]
	ds_read_b128 v[40:43], v29 offset:38976
	ds_read_b128 v[32:35], v25 offset:32768
	s_waitcnt lgkmcnt(3)
	v_mfma_f32_32x32x16_bf16 v[68:83], v[92:95], v[88:91], v[68:83]
	ds_read_b128 v[36:39], v25 offset:36864
	s_waitcnt lgkmcnt(3)
	v_mfma_f32_32x32x16_bf16 v[100:115], v[96:99], v[84:87], v[100:115]
	ds_read_b128 v[44:47], v29 offset:43072
	v_mfma_f32_32x32x16_bf16 v[4:19], v[96:99], v[88:91], v[4:19]
	s_waitcnt lgkmcnt(2)
	v_mfma_f32_32x32x16_bf16 v[116:131], v[40:43], v[32:35], v[116:131]
	s_waitcnt lgkmcnt(1)
	v_mfma_f32_32x32x16_bf16 v[68:83], v[40:43], v[36:39], v[68:83]
	s_waitcnt lgkmcnt(0)
	v_mfma_f32_32x32x16_bf16 v[100:115], v[44:47], v[32:35], v[100:115]
	v_mfma_f32_32x32x16_bf16 v[4:19], v[44:47], v[36:39], v[4:19]

; template <int NI, bool DEEP = true>
; DEV void gemm_tile(f32x16 (&acc)[2][NI], const bf16* __restrict__ A, int lda, const bf16* __restrict__ Bt, int ldb,
;                    int K, bf16* sA, bf16* sB) {
;     ...
;   G_LOAD(ra0, rb0, 0)
;   if (DEEP) {
;     if (64 < K) G_LOAD(ra1, rb1, 64)
;     for (int k0 = 0; k0 < K; k0 += 128) {
;       G_STEP(ra0, rb0, k0 + 128)
;       if (k0 + 64 < K) G_STEP(ra1, rb1, k0 + 192)
;     }
;   } else {
;     for (int k0 = 0; k0 < K; k0 += 64) G_STEP(ra0, rb0, k0 + 64)
;   }
; __device__ void phase_merge(PRef p, int l, const bf16* H2, bf16* M, bf16* sA, bf16* sB) {
;     ...
;       gemm_tile<2, false>(a1, U + (size_t)rt * 128 * ldu, ldu, p.WBO + ((size_t)n * 1024 + ct * 128) * 512, 512, 512, sA, sB);
.Lmbk_loop:
	s_waitcnt vmcnt(0)
	s_barrier
	ds_read_b128 v[156:159], v142 offset:0
	ds_read_b128 v[148:151], v138 offset:0
	ds_read_b128 v[152:155], v138 offset:4096
	ds_read_b128 v[160:163], v142 offset:4096
	s_waitcnt lgkmcnt(2)
	v_mfma_f32_32x32x16_bf16 v[84:99], v[156:159], v[148:151], v[84:99]
	s_add_u32 m0, s28, 0x8000
	s_nop 0
	global_load_lds_dwordx4 v134, s[98:99]
	ds_read_b128 v[172:175], v143 offset:0
	ds_read_b128 v[164:167], v139 offset:0
	s_waitcnt lgkmcnt(3)
	v_mfma_f32_32x32x16_bf16 v[36:51], v[156:159], v[152:155], v[36:51]
	s_add_u32 m0, s28, 0x8400
	s_add_u32 s34, s98, s0
	s_addc_u32 s35, s99, 0
	global_load_lds_dwordx4 v135, s[34:35]
	ds_read_b128 v[168:171], v139 offset:4096
	s_waitcnt lgkmcnt(3)
	v_mfma_f32_32x32x16_bf16 v[52:67], v[160:163], v[148:151], v[52:67]
	s_add_u32 m0, s28, 0x8800
	s_add_u32 s34, s34, s0
	s_addc_u32 s35, s35, 0
	global_load_lds_dwordx4 v134, s[34:35]
	ds_read_b128 v[176:179], v143 offset:4096
	v_mfma_f32_32x32x16_bf16 v[20:35], v[160:163], v[152:155], v[20:35]
	s_add_u32 m0, s28, 0x8c00
	s_add_u32 s34, s34, s0
	s_addc_u32 s35, s35, 0
	global_load_lds_dwordx4 v135, s[34:35]
	s_waitcnt lgkmcnt(2)
	v_mfma_f32_32x32x16_bf16 v[84:99], v[172:175], v[164:167], v[84:99]
	s_add_u32 m0, s28, 0xd840
	s_nop 0
	global_load_lds_dwordx4 v136, s[100:101]
	ds_read_b128 v[188:191], v144 offset:0
	ds_read_b128 v[180:183], v140 offset:0
	s_waitcnt lgkmcnt(3)
	v_mfma_f32_32x32x16_bf16 v[36:51], v[172:175], v[168:171], v[36:51]
	s_add_u32 m0, s28, 0xdc40
	s_add_u32 s34, s100, 0x2000
	s_addc_u32 s35, s101, 0
	global_load_lds_dwordx4 v137, s[34:35]
	ds_read_b128 v[184:187], v140 offset:4096
	s_waitcnt lgkmcnt(3)
	v_mfma_f32_32x32x16_bf16 v[52:67], v[176:179], v[164:167], v[52:67]
	s_add_u32 m0, s28, 0xe040
	s_add_u32 s34, s100, 0x4000
	s_addc_u32 s35, s101, 0
	global_load_lds_dwordx4 v136, s[34:35]
	ds_read_b128 v[210:213], v144 offset:4096
	v_mfma_f32_32x32x16_bf16 v[20:35], v[176:179], v[168:171], v[20:35]
	s_add_u32 m0, s28, 0xe440
	s_add_u32 s34, s100, 0x6000
	s_addc_u32 s35, s101, 0
	global_load_lds_dwordx4 v137, s[34:35]
	s_waitcnt lgkmcnt(2)
	v_mfma_f32_32x32x16_bf16 v[84:99], v[188:191], v[180:183], v[84:99]
	s_add_u32 s98, s98, 0x80
	s_addc_u32 s99, s99, 0
	s_add_u32 s100, s100, 0x80
	s_addc_u32 s101, s101, 0
	ds_read_b128 v[156:159], v145 offset:0
	ds_read_b128 v[148:151], v141 offset:0
	s_waitcnt lgkmcnt(3)
	v_mfma_f32_32x32x16_bf16 v[36:51], v[188:191], v[184:187], v[36:51]
	ds_read_b128 v[152:155], v141 offset:4096
	s_waitcnt lgkmcnt(3)
	v_mfma_f32_32x32x16_bf16 v[52:67], v[210:213], v[180:183], v[52:67]
	ds_read_b128 v[160:163], v145 offset:4096
	v_mfma_f32_32x32x16_bf16 v[20:35], v[210:213], v[184:187], v[20:35]
	s_waitcnt lgkmcnt(2)
	v_mfma_f32_32x32x16_bf16 v[84:99], v[156:159], v[148:151], v[84:99]
	s_waitcnt lgkmcnt(1)
	v_mfma_f32_32x32x16_bf16 v[36:51], v[156:159], v[152:155], v[36:51]
	s_waitcnt lgkmcnt(0)
	v_mfma_f32_32x32x16_bf16 v[52:67], v[160:163], v[148:151], v[52:67]
	v_mfma_f32_32x32x16_bf16 v[20:35], v[160:163], v[152:155], v[20:35]
	s_waitcnt vmcnt(0)
	s_barrier
	s_cmp_eq_u32 s57, 3
	s_cbranch_scc1 .Lmbk_nodma
	ds_read_b128 v[156:159], v142 offset:38976
	ds_read_b128 v[148:151], v138 offset:32768
	ds_read_b128 v[152:155], v138 offset:36864
	ds_read_b128 v[160:163], v142 offset:43072
	s_waitcnt lgkmcnt(2)
	v_mfma_f32_32x32x16_bf16 v[84:99], v[156:159], v[148:151], v[84:99]
	s_add_u32 m0, s28, 0x0
	s_nop 0
	global_load_lds_dwordx4 v134, s[98:99]
	ds_read_b128 v[172:175], v143 offset:38976
	ds_read_b128 v[164:167], v139 offset:32768
	s_waitcnt lgkmcnt(3)
	v_mfma_f32_32x32x16_bf16 v[36:51], v[156:159], v[152:155], v[36:51]
	s_add_u32 m0, s28, 0x400
	s_add_u32 s34, s98, s0
	s_addc_u32 s35, s99, 0
	global_load_lds_dwordx4 v135, s[34:35]
	ds_read_b128 v[168:171], v139 offset:36864
	s_waitcnt lgkmcnt(3)
	v_mfma_f32_32x32x16_bf16 v[52:67], v[160:163], v[148:151], v[52:67]
	s_add_u32 m0, s28, 0x800
	s_add_u32 s34, s34, s0
	s_addc_u32 s35, s35, 0
	global_load_lds_dwordx4 v134, s[34:35]
	ds_read_b128 v[176:179], v143 offset:43072
	v_mfma_f32_32x32x16_bf16 v[20:35], v[160:163], v[152:155], v[20:35]
	s_add_u32 m0, s28, 0xc00
	s_add_u32 s34, s34, s0
	s_addc_u32 s35, s35, 0
	global_load_lds_dwordx4 v135, s[34:35]
	s_waitcnt lgkmcnt(2)
	v_mfma_f32_32x32x16_bf16 v[84:99], v[172:175], v[164:167], v[84:99]
	s_add_u32 m0, s28, 0x4000
	s_nop 0
	global_load_lds_dwordx4 v136, s[100:101]
	ds_read_b128 v[188:191], v144 offset:38976
	ds_read_b128 v[180:183], v140 offset:32768
	s_waitcnt lgkmcnt(3)
	v_mfma_f32_32x32x16_bf16 v[36:51], v[172:175], v[168:171], v[36:51]
	s_add_u32 m0, s28, 0x4400
	s_add_u32 s34, s100, 0x2000
	s_addc_u32 s35, s101, 0
	global_load_lds_dwordx4 v137, s[34:35]
	ds_read_b128 v[184:187], v140 offset:36864
	s_waitcnt lgkmcnt(3)
	v_mfma_f32_32x32x16_bf16 v[52:67], v[176:179], v[164:167], v[52:67]
	s_add_u32 m0, s28, 0x4800
	s_add_u32 s34, s100, 0x4000
	s_addc_u32 s35, s101, 0
	global_load_lds_dwordx4 v136, s[34:35]
	ds_read_b128 v[210:213], v144 offset:43072
	v_mfma_f32_32x32x16_bf16 v[20:35], v[176:179], v[168:171], v[20:35]
	s_add_u32 m0, s28, 0x4c00
	s_add_u32 s34, s100, 0x6000
	s_addc_u32 s35, s101, 0
	global_load_lds_dwordx4 v137, s[34:35]
	s_waitcnt lgkmcnt(2)
	v_mfma_f32_32x32x16_bf16 v[84:99], v[188:191], v[180:183], v[84:99]
	s_add_u32 s98, s98, 0x80
	s_addc_u32 s99, s99, 0
	s_add_u32 s100, s100, 0x80
	s_addc_u32 s101, s101, 0
	ds_read_b128 v[156:159], v145 offset:38976
	ds_read_b128 v[148:151], v141 offset:32768
	s_waitcnt lgkmcnt(3)
	v_mfma_f32_32x32x16_bf16 v[36:51], v[188:191], v[184:187], v[36:51]
	ds_read_b128 v[152:155], v141 offset:36864
	s_waitcnt lgkmcnt(3)
	v_mfma_f32_32x32x16_bf16 v[52:67], v[210:213], v[180:183], v[52:67]
	ds_read_b128 v[160:163], v145 offset:43072
	v_mfma_f32_32x32x16_bf16 v[20:35], v[210:213], v[184:187], v[20:35]
	s_waitcnt lgkmcnt(2)
	v_mfma_f32_32x32x16_bf16 v[84:99], v[156:159], v[148:151], v[84:99]
	s_waitcnt lgkmcnt(1)
	v_mfma_f32_32x32x16_bf16 v[36:51], v[156:159], v[152:155], v[36:51]
	s_waitcnt lgkmcnt(0)
	v_mfma_f32_32x32x16_bf16 v[52:67], v[160:163], v[148:151], v[52:67]
	v_mfma_f32_32x32x16_bf16 v[20:35], v[160:163], v[152:155], v[20:35]
	s_branch .Lmbk_next
; template <int NI, bool DEEP = true>
; DEV void gemm_tile(f32x16 (&acc)[2][NI], const bf16* __restrict__ A, int lda, const bf16* __restrict__ Bt, int ldb,
;                    int K, bf16* sA, bf16* sB) {
;     ...
;     for (int k0 = 0; k0 < K; k0 += 64) G_STEP(ra0, rb0, k0 + 64)
.Lmbk_nodma:
	ds_read_b128 v[156:159], v142 offset:38976
	ds_read_b128 v[148:151], v138 offset:32768
	ds_read_b128 v[152:155], v138 offset:36864
	ds_read_b128 v[160:163], v142 offset:43072
	s_waitcnt lgkmcnt(2)
	v_mfma_f32_32x32x16_bf16 v[84:99], v[156:159], v[148:151], v[84:99]
	ds_read_b128 v[172:175], v143 offset:38976
	ds_read_b128 v[164:167], v139 offset:32768
	s_waitcnt lgkmcnt(3)
	v_mfma_f32_32x32x16_bf16 v[36:51], v[156:159], v[152:155], v[36:51]
	ds_read_b128 v[168:171], v139 offset:36864
	s_waitcnt lgkmcnt(3)
	v_mfma_f32_32x32x16_bf16 v[52:67], v[160:163], v[148:151], v[52:67]
	ds_read_b128 v[176:179], v143 offset:43072
	v_mfma_f32_32x32x16_bf16 v[20:35], v[160:163], v[152:155], v[20:35]
	s_waitcnt lgkmcnt(2)
	v_mfma_f32_32x32x16_bf16 v[84:99], v[172:175], v[164:167], v[84:99]
	ds_read_b128 v[188:191], v144 offset:38976
	ds_read_b128 v[180:183], v140 offset:32768
	s_waitcnt lgkmcnt(3)
	v_mfma_f32_32x32x16_bf16 v[36:51], v[172:175], v[168:171], v[36:51]
	ds_read_b128 v[184:187], v140 offset:36864
	s_waitcnt lgkmcnt(3)
	v_mfma_f32_32x32x16_bf16 v[52:67], v[176:179], v[164:167], v[52:67]
	ds_read_b128 v[210:213], v144 offset:43072
	v_mfma_f32_32x32x16_bf16 v[20:35], v[176:179], v[168:171], v[20:35]
	s_waitcnt lgkmcnt(2)
	v_mfma_f32_32x32x16_bf16 v[84:99], v[188:191], v[180:183], v[84:99]
	ds_read_b128 v[156:159], v145 offset:38976
	ds_read_b128 v[148:151], v141 offset:32768
	s_waitcnt lgkmcnt(3)
	v_mfma_f32_32x32x16_bf16 v[36:51], v[188:191], v[184:187], v[36:51]
	ds_read_b128 v[152:155], v141 offset:36864
	s_waitcnt lgkmcnt(3)
	v_mfma_f32_32x32x16_bf16 v[52:67], v[210:213], v[180:183], v[52:67]
	ds_read_b128 v[160:163], v145 offset:43072
	v_mfma_f32_32x32x16_bf16 v[20:35], v[210:213], v[184:187], v[20:35]
	s_waitcnt lgkmcnt(2)
	v_mfma_f32_32x32x16_bf16 v[84:99], v[156:159], v[148:151], v[84:99]
	s_waitcnt lgkmcnt(1)
	v_mfma_f32_32x32x16_bf16 v[36:51], v[156:159], v[152:155], v[36:51]
	s_waitcnt lgkmcnt(0)
	v_mfma_f32_32x32x16_bf16 v[52:67], v[160:163], v[148:151], v[52:67]
	v_mfma_f32_32x32x16_bf16 v[20:35], v[160:163], v[152:155], v[20:35]

; DEV float bflo(uint32_t u) { return __uint_as_float(u << 16); }
; DEV float bfhi(uint32_t u) { return __uint_as_float(u & 0xffff0000u); }
; __device__ void phase_merge(PRef p, int l, const bf16* H2, bf16* M, bf16* sA, bf16* sB) {
;     ...
; #pragma unroll
;         for (int a = 0; a < 2; a++)
; #pragma unroll
;           for (int bb = 0; bb < 2; bb++)
; #pragma unroll
;             for (int r = 0; r < 8; r++) {
;               float g0 = __fdividef(1.f, 1.f + __expf(-a2[a][bb][2 * r]));
;               float g1 = __fdividef(1.f, 1.f + __expf(-a2[a][bb][2 * r + 1]));
;               gp[a][bb][r] = pack2(g0, g1);
;             }
;       }
;       f32x16 a1[2][2];
;       zero_acc<2>(a1);
;       gemm_tile<2, false>(a1, U + (size_t)rt * 128 * ldu, ldu, p.WBO + ((size_t)n * 1024 + ct * 128) * 512, 512, 512, sA, sB);
; #pragma unroll
;       for (int a = 0; a < 2; a++)
; #pragma unroll
;         for (int bb = 0; bb < 2; bb++)
; #pragma unroll
;           for (int r = 0; r < 8; r++) {
;             a1[a][bb][2 * r] *= bflo(gp[a][bb][r]);
;             a1[a][bb][2 * r + 1] *= bfhi(gp[a][bb][r]);
;           }
.LBB0_972:
	s_cmp_lg_u32 s95, 0
	s_cselect_b64 s[54:55], -1, 0
	v_mul_f32_e32 v116, 0xbfb8aa3b, v116
	v_mul_f32_e32 v117, 0xbfb8aa3b, v117
	v_mul_f32_e32 v118, 0xbfb8aa3b, v118
	v_mul_f32_e32 v119, 0xbfb8aa3b, v119
	v_mul_f32_e32 v120, 0xbfb8aa3b, v120
	v_mul_f32_e32 v121, 0xbfb8aa3b, v121
	v_mul_f32_e32 v122, 0xbfb8aa3b, v122
	v_mul_f32_e32 v123, 0xbfb8aa3b, v123
	v_exp_f32_e32 v116, v116
	v_exp_f32_e32 v117, v117
	v_exp_f32_e32 v118, v118
	v_exp_f32_e32 v119, v119
	v_exp_f32_e32 v120, v120
	v_exp_f32_e32 v121, v121
	v_exp_f32_e32 v122, v122
	v_exp_f32_e32 v123, v123
	v_add_f32_e32 v116, 1.0, v116
	v_add_f32_e32 v117, 1.0, v117
	v_add_f32_e32 v118, 1.0, v118
	v_add_f32_e32 v119, 1.0, v119
	v_add_f32_e32 v120, 1.0, v120
	v_add_f32_e32 v121, 1.0, v121
	v_add_f32_e32 v122, 1.0, v122
	v_add_f32_e32 v123, 1.0, v123
	v_rcp_f32_e32 v116, v116
	v_rcp_f32_e32 v117, v117
	v_rcp_f32_e32 v118, v118
	v_rcp_f32_e32 v119, v119
	v_rcp_f32_e32 v120, v120
	v_rcp_f32_e32 v121, v121
	v_rcp_f32_e32 v122, v122
	v_rcp_f32_e32 v123, v123
	v_mul_f32_e32 v84, v84, v116
	v_mul_f32_e32 v85, v85, v117
	v_mul_f32_e32 v86, v86, v118
	v_mul_f32_e32 v87, v87, v119
	v_mul_f32_e32 v88, v88, v120
	v_mul_f32_e32 v89, v89, v121
	v_mul_f32_e32 v90, v90, v122
	v_mul_f32_e32 v91, v91, v123
	v_mul_f32_e32 v124, 0xbfb8aa3b, v124
	v_mul_f32_e32 v125, 0xbfb8aa3b, v125
	v_mul_f32_e32 v126, 0xbfb8aa3b, v126
	v_mul_f32_e32 v127, 0xbfb8aa3b, v127
	v_mul_f32_e32 v128, 0xbfb8aa3b, v128
	v_mul_f32_e32 v129, 0xbfb8aa3b, v129
	v_mul_f32_e32 v130, 0xbfb8aa3b, v130
	v_mul_f32_e32 v131, 0xbfb8aa3b, v131
	v_exp_f32_e32 v124, v124
	v_exp_f32_e32 v125, v125
	v_exp_f32_e32 v126, v126
	v_exp_f32_e32 v127, v127
	v_exp_f32_e32 v128, v128
	v_exp_f32_e32 v129, v129
	v_exp_f32_e32 v130, v130
	v_exp_f32_e32 v131, v131
	v_add_f32_e32 v124, 1.0, v124
	v_add_f32_e32 v125, 1.0, v125
	v_add_f32_e32 v126, 1.0, v126
	v_add_f32_e32 v127, 1.0, v127
	v_add_f32_e32 v128, 1.0, v128
	v_add_f32_e32 v129, 1.0, v129
	v_add_f32_e32 v130, 1.0, v130
	v_add_f32_e32 v131, 1.0, v131
	v_rcp_f32_e32 v124, v124
	v_rcp_f32_e32 v125, v125
	v_rcp_f32_e32 v126, v126
	v_rcp_f32_e32 v127, v127
	v_rcp_f32_e32 v128, v128
	v_rcp_f32_e32 v129, v129
	v_rcp_f32_e32 v130, v130
	v_rcp_f32_e32 v131, v131
	v_mul_f32_e32 v92, v92, v124
	v_mul_f32_e32 v93, v93, v125
	v_mul_f32_e32 v94, v94, v126
	v_mul_f32_e32 v95, v95, v127
	v_mul_f32_e32 v96, v96, v128
	v_mul_f32_e32 v97, v97, v129
	v_mul_f32_e32 v98, v98, v130
	v_mul_f32_e32 v99, v99, v131
	v_mul_f32_e32 v100, 0xbfb8aa3b, v100
	v_mul_f32_e32 v101, 0xbfb8aa3b, v101
	v_mul_f32_e32 v102, 0xbfb8aa3b, v102
	v_mul_f32_e32 v103, 0xbfb8aa3b, v103
	v_mul_f32_e32 v104, 0xbfb8aa3b, v104
	v_mul_f32_e32 v105, 0xbfb8aa3b, v105
	v_mul_f32_e32 v106, 0xbfb8aa3b, v106
	v_mul_f32_e32 v107, 0xbfb8aa3b, v107
	v_exp_f32_e32 v100, v100
	v_exp_f32_e32 v101, v101
	v_exp_f32_e32 v102, v102
	v_exp_f32_e32 v103, v103
	v_exp_f32_e32 v104, v104
	v_exp_f32_e32 v105, v105
	v_exp_f32_e32 v106, v106
	v_exp_f32_e32 v107, v107
	v_add_f32_e32 v100, 1.0, v100
	v_add_f32_e32 v101, 1.0, v101
	v_add_f32_e32 v102, 1.0, v102
	v_add_f32_e32 v103, 1.0, v103
	v_add_f32_e32 v104, 1.0, v104
	v_add_f32_e32 v105, 1.0, v105
	v_add_f32_e32 v106, 1.0, v106
	v_add_f32_e32 v107, 1.0, v107
	v_rcp_f32_e32 v100, v100
	v_rcp_f32_e32 v101, v101
	v_rcp_f32_e32 v102, v102
	v_rcp_f32_e32 v103, v103
	v_rcp_f32_e32 v104, v104
	v_rcp_f32_e32 v105, v105
	v_rcp_f32_e32 v106, v106
	v_rcp_f32_e32 v107, v107
	v_mul_f32_e32 v52, v52, v100
	v_mul_f32_e32 v53, v53, v101
	v_mul_f32_e32 v54, v54, v102
	v_mul_f32_e32 v55, v55, v103
	v_mul_f32_e32 v56, v56, v104
	v_mul_f32_e32 v57, v57, v105
	v_mul_f32_e32 v58, v58, v106
	v_mul_f32_e32 v59, v59, v107
	v_mul_f32_e32 v108, 0xbfb8aa3b, v108
	v_mul_f32_e32 v109, 0xbfb8aa3b, v109
	v_mul_f32_e32 v110, 0xbfb8aa3b, v110
	v_mul_f32_e32 v111, 0xbfb8aa3b, v111
	v_mul_f32_e32 v112, 0xbfb8aa3b, v112
	v_mul_f32_e32 v113, 0xbfb8aa3b, v113
	v_mul_f32_e32 v114, 0xbfb8aa3b, v114
	v_mul_f32_e32 v115, 0xbfb8aa3b, v115
	v_exp_f32_e32 v108, v108
	v_exp_f32_e32 v109, v109
	v_exp_f32_e32 v110, v110
	v_exp_f32_e32 v111, v111
	v_exp_f32_e32 v112, v112
	v_exp_f32_e32 v113, v113
	v_exp_f32_e32 v114, v114
	v_exp_f32_e32 v115, v115
	v_add_f32_e32 v108, 1.0, v108
	v_add_f32_e32 v109, 1.0, v109
	v_add_f32_e32 v110, 1.0, v110
	v_add_f32_e32 v111, 1.0, v111
	v_add_f32_e32 v112, 1.0, v112
	v_add_f32_e32 v113, 1.0, v113
	v_add_f32_e32 v114, 1.0, v114
	v_add_f32_e32 v115, 1.0, v115
	v_rcp_f32_e32 v108, v108
	v_rcp_f32_e32 v109, v109
	v_rcp_f32_e32 v110, v110
	v_rcp_f32_e32 v111, v111
	v_rcp_f32_e32 v112, v112
	v_rcp_f32_e32 v113, v113
	v_rcp_f32_e32 v114, v114
	v_rcp_f32_e32 v115, v115
	v_mul_f32_e32 v60, v60, v108
	v_mul_f32_e32 v61, v61, v109
	v_mul_f32_e32 v62, v62, v110
	v_mul_f32_e32 v63, v63, v111
	v_mul_f32_e32 v64, v64, v112
	v_mul_f32_e32 v65, v65, v113
	v_mul_f32_e32 v66, v66, v114
	v_mul_f32_e32 v67, v67, v115
	v_mul_f32_e32 v68, 0xbfb8aa3b, v68
	v_mul_f32_e32 v69, 0xbfb8aa3b, v69
	v_mul_f32_e32 v70, 0xbfb8aa3b, v70
	v_mul_f32_e32 v71, 0xbfb8aa3b, v71
	v_mul_f32_e32 v72, 0xbfb8aa3b, v72
	v_mul_f32_e32 v73, 0xbfb8aa3b, v73
	v_mul_f32_e32 v74, 0xbfb8aa3b, v74
	v_mul_f32_e32 v75, 0xbfb8aa3b, v75
	v_exp_f32_e32 v68, v68
	v_exp_f32_e32 v69, v69
	v_exp_f32_e32 v70, v70
	v_exp_f32_e32 v71, v71
	v_exp_f32_e32 v72, v72
	v_exp_f32_e32 v73, v73
	v_exp_f32_e32 v74, v74
	v_exp_f32_e32 v75, v75
	v_add_f32_e32 v68, 1.0, v68
	v_add_f32_e32 v69, 1.0, v69
	v_add_f32_e32 v70, 1.0, v70
	v_add_f32_e32 v71, 1.0, v71
	v_add_f32_e32 v72, 1.0, v72
	v_add_f32_e32 v73, 1.0, v73
	v_add_f32_e32 v74, 1.0, v74
	v_add_f32_e32 v75, 1.0, v75
	v_rcp_f32_e32 v68, v68
; DEV int tid_() { int t = threadIdx.x; asm volatile("" : "+v"(t)); return t; }
; DEV float bflo(uint32_t u) { return __uint_as_float(u << 16); }
; DEV float bfhi(uint32_t u) { return __uint_as_float(u & 0xffff0000u); }
; template <int NI>
; DEV void stage_tile(const f32x16 (&acc)[2][NI], bf16* sC) {
;   constexpr int LDC = NI * 64 + 8;
;   int tid = tid_();
;   int lane = tid & 63, wave = tid >> 6;
;   int wm = wave >> 1, wn = wave & 1;
;   __syncthreads();
; #pragma unroll
;   for (int mi = 0; mi < 2; mi++)
; #pragma unroll
;     for (int ni = 0; ni < NI; ni++)
; #pragma unroll
;       for (int g = 0; g < 4; g++) {
;         int row = wm * 64 + mi * 32 + (lane & 31);
;         int col = wn * NI * 32 + ni * 32 + 8 * g + 4 * (lane >> 5);
;         uint2 v;
;         v.x = pack2(acc[mi][ni][4 * g], acc[mi][ni][4 * g + 1]);
;         v.y = pack2(acc[mi][ni][4 * g + 2], acc[mi][ni][4 * g + 3]);
;         *(uint2*)(sC + row * LDC + col) = v;
;       }
;   __syncthreads();
; }
; __device__ void phase_merge(PRef p, int l, const bf16* H2, bf16* M, bf16* sA, bf16* sB) {
;     ...
; #pragma unroll
;       for (int a = 0; a < 2; a++)
; #pragma unroll
;         for (int bb = 0; bb < 2; bb++)
; #pragma unroll
;           for (int r = 0; r < 8; r++) {
;             a1[a][bb][2 * r] *= bflo(gp[a][bb][r]);
;             a1[a][bb][2 * r + 1] *= bfhi(gp[a][bb][r]);
;           }
;       stage_tile<2>(a1, sA);
	v_rcp_f32_e32 v69, v69
	v_rcp_f32_e32 v70, v70
	v_rcp_f32_e32 v71, v71
	v_rcp_f32_e32 v72, v72
	v_rcp_f32_e32 v73, v73
	v_rcp_f32_e32 v74, v74
	v_rcp_f32_e32 v75, v75
	v_mul_f32_e32 v36, v36, v68
	v_mul_f32_e32 v37, v37, v69
	v_mul_f32_e32 v38, v38, v70
	v_mul_f32_e32 v39, v39, v71
	v_mul_f32_e32 v40, v40, v72
	v_mul_f32_e32 v41, v41, v73
	v_mul_f32_e32 v42, v42, v74
	v_mul_f32_e32 v43, v43, v75
	v_mul_f32_e32 v76, 0xbfb8aa3b, v76
	v_mul_f32_e32 v77, 0xbfb8aa3b, v77
	v_mul_f32_e32 v78, 0xbfb8aa3b, v78
	v_mul_f32_e32 v79, 0xbfb8aa3b, v79
	v_mul_f32_e32 v80, 0xbfb8aa3b, v80
	v_mul_f32_e32 v81, 0xbfb8aa3b, v81
	v_mul_f32_e32 v82, 0xbfb8aa3b, v82
	v_mul_f32_e32 v83, 0xbfb8aa3b, v83
	v_exp_f32_e32 v76, v76
	v_exp_f32_e32 v77, v77
	v_exp_f32_e32 v78, v78
	v_exp_f32_e32 v79, v79
	v_exp_f32_e32 v80, v80
	v_exp_f32_e32 v81, v81
	v_exp_f32_e32 v82, v82
	v_exp_f32_e32 v83, v83
	v_add_f32_e32 v76, 1.0, v76
	v_add_f32_e32 v77, 1.0, v77
	v_add_f32_e32 v78, 1.0, v78
	v_add_f32_e32 v79, 1.0, v79
	v_add_f32_e32 v80, 1.0, v80
	v_add_f32_e32 v81, 1.0, v81
	v_add_f32_e32 v82, 1.0, v82
	v_add_f32_e32 v83, 1.0, v83
	v_rcp_f32_e32 v76, v76
	v_rcp_f32_e32 v77, v77
	v_rcp_f32_e32 v78, v78
	v_rcp_f32_e32 v79, v79
	v_rcp_f32_e32 v80, v80
	v_rcp_f32_e32 v81, v81
	v_rcp_f32_e32 v82, v82
	v_rcp_f32_e32 v83, v83
	v_mul_f32_e32 v44, v44, v76
	v_mul_f32_e32 v45, v45, v77
	v_mul_f32_e32 v46, v46, v78
	v_mul_f32_e32 v47, v47, v79
	v_mul_f32_e32 v48, v48, v80
	v_mul_f32_e32 v49, v49, v81
	v_mul_f32_e32 v50, v50, v82
	v_mul_f32_e32 v51, v51, v83
	v_mul_f32_e32 v4, 0xbfb8aa3b, v4
	v_mul_f32_e32 v5, 0xbfb8aa3b, v5
	v_mul_f32_e32 v6, 0xbfb8aa3b, v6
	v_mul_f32_e32 v7, 0xbfb8aa3b, v7
	v_mul_f32_e32 v8, 0xbfb8aa3b, v8
	v_mul_f32_e32 v9, 0xbfb8aa3b, v9
	v_mul_f32_e32 v10, 0xbfb8aa3b, v10
	v_mul_f32_e32 v11, 0xbfb8aa3b, v11
	v_exp_f32_e32 v4, v4
	v_exp_f32_e32 v5, v5
	v_exp_f32_e32 v6, v6
	v_exp_f32_e32 v7, v7
	v_exp_f32_e32 v8, v8
	v_exp_f32_e32 v9, v9
	v_exp_f32_e32 v10, v10
	v_exp_f32_e32 v11, v11
	v_add_f32_e32 v4, 1.0, v4
	v_add_f32_e32 v5, 1.0, v5
	v_add_f32_e32 v6, 1.0, v6
	v_add_f32_e32 v7, 1.0, v7
	v_add_f32_e32 v8, 1.0, v8
	v_add_f32_e32 v9, 1.0, v9
	v_add_f32_e32 v10, 1.0, v10
	v_add_f32_e32 v11, 1.0, v11
	v_rcp_f32_e32 v4, v4
	v_rcp_f32_e32 v5, v5
	v_rcp_f32_e32 v6, v6
	v_rcp_f32_e32 v7, v7
	v_rcp_f32_e32 v8, v8
	v_rcp_f32_e32 v9, v9
	v_rcp_f32_e32 v10, v10
	v_rcp_f32_e32 v11, v11
	v_mul_f32_e32 v20, v20, v4
	v_mul_f32_e32 v21, v21, v5
	v_mul_f32_e32 v22, v22, v6
	v_mul_f32_e32 v23, v23, v7
	v_mul_f32_e32 v24, v24, v8
	v_mul_f32_e32 v25, v25, v9
	v_mul_f32_e32 v26, v26, v10
	v_mul_f32_e32 v27, v27, v11
	v_mul_f32_e32 v12, 0xbfb8aa3b, v12
	v_mul_f32_e32 v13, 0xbfb8aa3b, v13
	v_mul_f32_e32 v14, 0xbfb8aa3b, v14
	v_mul_f32_e32 v15, 0xbfb8aa3b, v15
	v_mul_f32_e32 v16, 0xbfb8aa3b, v16
	v_mul_f32_e32 v17, 0xbfb8aa3b, v17
	v_mul_f32_e32 v18, 0xbfb8aa3b, v18
	v_mul_f32_e32 v19, 0xbfb8aa3b, v19
	v_exp_f32_e32 v12, v12
	v_exp_f32_e32 v13, v13
	v_exp_f32_e32 v14, v14
	v_exp_f32_e32 v15, v15
	v_exp_f32_e32 v16, v16
	v_exp_f32_e32 v17, v17
	v_exp_f32_e32 v18, v18
	v_exp_f32_e32 v19, v19
	v_add_f32_e32 v12, 1.0, v12
	v_add_f32_e32 v13, 1.0, v13
	v_add_f32_e32 v14, 1.0, v14
	v_add_f32_e32 v15, 1.0, v15
	v_add_f32_e32 v16, 1.0, v16
	v_add_f32_e32 v17, 1.0, v17
	v_add_f32_e32 v18, 1.0, v18
	v_add_f32_e32 v19, 1.0, v19
	v_rcp_f32_e32 v12, v12
	v_rcp_f32_e32 v13, v13
	v_rcp_f32_e32 v14, v14
	v_rcp_f32_e32 v15, v15
	v_rcp_f32_e32 v16, v16
	v_rcp_f32_e32 v17, v17
	v_rcp_f32_e32 v18, v18
	v_rcp_f32_e32 v19, v19
	v_mul_f32_e32 v28, v28, v12
	v_mul_f32_e32 v29, v29, v13
	v_mul_f32_e32 v30, v30, v14
	v_mul_f32_e32 v31, v31, v15
	v_mul_f32_e32 v32, v32, v16
	v_mul_f32_e32 v33, v33, v17
	v_mul_f32_e32 v34, v34, v18
	v_mul_f32_e32 v35, v35, v19
	v_lshrrev_b32_e32 v0, 6, v196
	v_and_b32_e32 v1, 31, v196
	v_lshrrev_b32_e32 v2, 1, v0
	v_lshl_add_u32 v1, v2, 6, v1
	v_mul_u32_u24_e32 v1, 0x110, v1
	v_and_b32_e32 v0, 1, v0
	v_lshl_add_u32 v1, v0, 7, v1
	v_bfe_u32 v0, v196, 5, 1
	v_lshl_add_u32 v2, v0, 3, v1
	v_cvt_pk_bf16_f32 v84, v84, v85
	v_cvt_pk_bf16_f32 v85, v86, v87
	v_cvt_pk_bf16_f32 v88, v88, v89
	v_cvt_pk_bf16_f32 v89, v90, v91
	v_cvt_pk_bf16_f32 v92, v92, v93
	v_cvt_pk_bf16_f32 v93, v94, v95
	v_cvt_pk_bf16_f32 v96, v96, v97
	v_cvt_pk_bf16_f32 v97, v98, v99
	v_cvt_pk_bf16_f32 v52, v52, v53
	v_cvt_pk_bf16_f32 v53, v54, v55
	v_cvt_pk_bf16_f32 v56, v56, v57
	v_cvt_pk_bf16_f32 v57, v58, v59
	v_cvt_pk_bf16_f32 v60, v60, v61
	v_cvt_pk_bf16_f32 v61, v62, v63
	v_cvt_pk_bf16_f32 v64, v64, v65
	v_cvt_pk_bf16_f32 v65, v66, v67
	v_cvt_pk_bf16_f32 v36, v36, v37
	v_cvt_pk_bf16_f32 v37, v38, v39
	v_cvt_pk_bf16_f32 v40, v40, v41
	v_cvt_pk_bf16_f32 v41, v42, v43
	v_cvt_pk_bf16_f32 v44, v44, v45
	v_cvt_pk_bf16_f32 v45, v46, v47
	v_cvt_pk_bf16_f32 v48, v48, v49
	v_cvt_pk_bf16_f32 v49, v50, v51
	v_cvt_pk_bf16_f32 v20, v20, v21
	v_cvt_pk_bf16_f32 v21, v22, v23
	v_cvt_pk_bf16_f32 v24, v24, v25
	v_cvt_pk_bf16_f32 v25, v26, v27
	v_cvt_pk_bf16_f32 v28, v28, v29
	v_cvt_pk_bf16_f32 v29, v30, v31
	v_cvt_pk_bf16_f32 v32, v32, v33
	v_cvt_pk_bf16_f32 v33, v34, v35
	s_waitcnt lgkmcnt(0)
	s_barrier
	ds_write_b64 v2, v[84:85] offset:0
	ds_write_b64 v2, v[88:89] offset:16
	ds_write_b64 v2, v[92:93] offset:32
	ds_write_b64 v2, v[96:97] offset:48
	ds_write_b64 v2, v[52:53] offset:64
	ds_write_b64 v2, v[56:57] offset:80
	ds_write_b64 v2, v[60:61] offset:96
	ds_write_b64 v2, v[64:65] offset:112
	ds_write_b64 v2, v[36:37] offset:8704
	ds_write_b64 v2, v[40:41] offset:8720
	ds_write_b64 v2, v[44:45] offset:8736
	ds_write_b64 v2, v[48:49] offset:8752
	ds_write_b64 v2, v[20:21] offset:8768
	ds_write_b64 v2, v[24:25] offset:8784
	ds_write_b64 v2, v[28:29] offset:8800
	ds_write_b64 v2, v[32:33] offset:8816
	s_waitcnt lgkmcnt(0)
	s_barrier
; DEV float bflo(uint32_t u) { return __uint_as_float(u << 16); }
; DEV float bfhi(uint32_t u) { return __uint_as_float(u & 0xffff0000u); }
; __device__ void phase_merge(PRef p, int l, const bf16* H2, bf16* M, bf16* sA, bf16* sB) {
;     ...
;       TILE_CHUNKS(2, sA, {
;         u32x4* mp = (u32x4*)(M + (size_t)(rt * 128 + trow) * 1024 + ct * 128 + tcol);
;         u32x4 ov = cv;
;         if (n != 0) {
;           u32x4 pv = *mp;
;           _Pragma("unroll") for (int j = 0; j < 4; j++) ov[j] = pack2(bflo(pv[j]) + bflo(cv[j]), bfhi(pv[j]) + bfhi(cv[j]));
;         }
;         *mp = ov;
;       })
	v_lshrrev_b32_e32 v60, 4, v196
	v_and_b32_e32 v61, 15, v196
	v_mul_lo_u32 v62, v60, s52
	v_lshl_add_u32 v62, v61, 4, v62
	v_lshlrev_b32_e32 v63, 11, v60
	v_lshl_add_u32 v63, v61, 4, v63
	s_lshl_b32 s0, s94, 11
	s_add_u32 s98, s22, s0
	s_addc_u32 s99, s23, 0
	s_mov_b64 s[100:101], s[98:99]
	s_and_b64 vcc, exec, s[54:55]
	s_cbranch_vccz .Lmerge_first
	global_load_dwordx4 v[20:23], v63, s[98:99]
	s_add_u32 s98, s98, 0x8000
	s_addc_u32 s99, s99, 0
	global_load_dwordx4 v[24:27], v63, s[98:99]
	s_add_u32 s98, s98, 0x8000
	s_addc_u32 s99, s99, 0
	global_load_dwordx4 v[28:31], v63, s[98:99]
	s_add_u32 s98, s98, 0x8000
	s_addc_u32 s99, s99, 0
	global_load_dwordx4 v[32:35], v63, s[98:99]
	s_add_u32 s98, s98, 0x8000
	s_addc_u32 s99, s99, 0
	global_load_dwordx4 v[36:39], v63, s[98:99]
	s_add_u32 s98, s98, 0x8000
	s_addc_u32 s99, s99, 0
	global_load_dwordx4 v[40:43], v63, s[98:99]
	s_add_u32 s98, s98, 0x8000
	s_addc_u32 s99, s99, 0
	global_load_dwordx4 v[44:47], v63, s[98:99]
	s_add_u32 s98, s98, 0x8000
	s_addc_u32 s99, s99, 0
	global_load_dwordx4 v[48:51], v63, s[98:99]
	ds_read_b128 v[4:7], v62 offset:0
	s_waitcnt vmcnt(7) lgkmcnt(0)
	v_lshlrev_b32_e32 v8, 16, v4
	v_and_b32_e32 v9, 0xffff0000, v4
	v_lshlrev_b32_e32 v10, 16, v5
	v_and_b32_e32 v11, 0xffff0000, v5
	v_lshlrev_b32_e32 v12, 16, v6
	v_and_b32_e32 v13, 0xffff0000, v6
	v_lshlrev_b32_e32 v14, 16, v7
	v_and_b32_e32 v15, 0xffff0000, v7
	v_lshlrev_b32_e32 v52, 16, v20
	v_and_b32_e32 v53, 0xffff0000, v20
	v_lshlrev_b32_e32 v54, 16, v21
	v_and_b32_e32 v55, 0xffff0000, v21
	v_lshlrev_b32_e32 v56, 16, v22
	v_and_b32_e32 v57, 0xffff0000, v22
	v_lshlrev_b32_e32 v58, 16, v23
	v_and_b32_e32 v59, 0xffff0000, v23
	v_add_f32_e32 v8, v8, v52
	v_add_f32_e32 v9, v9, v53
	v_add_f32_e32 v10, v10, v54
	v_add_f32_e32 v11, v11, v55
	v_add_f32_e32 v12, v12, v56
	v_add_f32_e32 v13, v13, v57
	v_add_f32_e32 v14, v14, v58
	v_add_f32_e32 v15, v15, v59
	v_cvt_pk_bf16_f32 v20, v8, v9
	v_cvt_pk_bf16_f32 v21, v10, v11
	v_cvt_pk_bf16_f32 v22, v12, v13
	v_cvt_pk_bf16_f32 v23, v14, v15
	global_store_dwordx4 v63, v[20:23], s[100:101]
	s_add_u32 s100, s100, 0x8000
	s_addc_u32 s101, s101, 0
	ds_read_b128 v[4:7], v62 offset:4352
	s_waitcnt vmcnt(7) lgkmcnt(0)
	v_lshlrev_b32_e32 v8, 16, v4
	v_and_b32_e32 v9, 0xffff0000, v4
	v_lshlrev_b32_e32 v10, 16, v5
	v_and_b32_e32 v11, 0xffff0000, v5
	v_lshlrev_b32_e32 v12, 16, v6
	v_and_b32_e32 v13, 0xffff0000, v6
	v_lshlrev_b32_e32 v14, 16, v7
	v_and_b32_e32 v15, 0xffff0000, v7
	v_lshlrev_b32_e32 v52, 16, v24
	v_and_b32_e32 v53, 0xffff0000, v24
	v_lshlrev_b32_e32 v54, 16, v25
	v_and_b32_e32 v55, 0xffff0000, v25
	v_lshlrev_b32_e32 v56, 16, v26
	v_and_b32_e32 v57, 0xffff0000, v26
	v_lshlrev_b32_e32 v58, 16, v27
	v_and_b32_e32 v59, 0xffff0000, v27
	v_add_f32_e32 v8, v8, v52
	v_add_f32_e32 v9, v9, v53
	v_add_f32_e32 v10, v10, v54
	v_add_f32_e32 v11, v11, v55
	v_add_f32_e32 v12, v12, v56
	v_add_f32_e32 v13, v13, v57
	v_add_f32_e32 v14, v14, v58
	v_add_f32_e32 v15, v15, v59
	v_cvt_pk_bf16_f32 v24, v8, v9
	v_cvt_pk_bf16_f32 v25, v10, v11
	v_cvt_pk_bf16_f32 v26, v12, v13
	v_cvt_pk_bf16_f32 v27, v14, v15
	global_store_dwordx4 v63, v[24:27], s[100:101]
	s_add_u32 s100, s100, 0x8000
	s_addc_u32 s101, s101, 0
	ds_read_b128 v[4:7], v62 offset:8704
	s_waitcnt vmcnt(7) lgkmcnt(0)
	v_lshlrev_b32_e32 v8, 16, v4
	v_and_b32_e32 v9, 0xffff0000, v4
	v_lshlrev_b32_e32 v10, 16, v5
	v_and_b32_e32 v11, 0xffff0000, v5
	v_lshlrev_b32_e32 v12, 16, v6
	v_and_b32_e32 v13, 0xffff0000, v6
	v_lshlrev_b32_e32 v14, 16, v7
	v_and_b32_e32 v15, 0xffff0000, v7
	v_lshlrev_b32_e32 v52, 16, v28
	v_and_b32_e32 v53, 0xffff0000, v28
	v_lshlrev_b32_e32 v54, 16, v29
	v_and_b32_e32 v55, 0xffff0000, v29
	v_lshlrev_b32_e32 v56, 16, v30
	v_and_b32_e32 v57, 0xffff0000, v30
	v_lshlrev_b32_e32 v58, 16, v31
	v_and_b32_e32 v59, 0xffff0000, v31
	v_add_f32_e32 v8, v8, v52
	v_add_f32_e32 v9, v9, v53
	v_add_f32_e32 v10, v10, v54
	v_add_f32_e32 v11, v11, v55
	v_add_f32_e32 v12, v12, v56
	v_add_f32_e32 v13, v13, v57
	v_add_f32_e32 v14, v14, v58
	v_add_f32_e32 v15, v15, v59
	v_cvt_pk_bf16_f32 v28, v8, v9
	v_cvt_pk_bf16_f32 v29, v10, v11
	v_cvt_pk_bf16_f32 v30, v12, v13
	v_cvt_pk_bf16_f32 v31, v14, v15
	global_store_dwordx4 v63, v[28:31], s[100:101]
	s_add_u32 s100, s100, 0x8000
	s_addc_u32 s101, s101, 0
	ds_read_b128 v[4:7], v62 offset:13056
	s_waitcnt vmcnt(7) lgkmcnt(0)
; DEV float bflo(uint32_t u) { return __uint_as_float(u << 16); }
; DEV float bfhi(uint32_t u) { return __uint_as_float(u & 0xffff0000u); }
; __device__ void phase_merge(PRef p, int l, const bf16* H2, bf16* M, bf16* sA, bf16* sB) {
;     ...
;       TILE_CHUNKS(2, sA, {
;         u32x4* mp = (u32x4*)(M + (size_t)(rt * 128 + trow) * 1024 + ct * 128 + tcol);
;         u32x4 ov = cv;
;         if (n != 0) {
;           u32x4 pv = *mp;
;           _Pragma("unroll") for (int j = 0; j < 4; j++) ov[j] = pack2(bflo(pv[j]) + bflo(cv[j]), bfhi(pv[j]) + bfhi(cv[j]));
;         }
;         *mp = ov;
;       })
	v_lshlrev_b32_e32 v8, 16, v4
	v_and_b32_e32 v9, 0xffff0000, v4
	v_lshlrev_b32_e32 v10, 16, v5
	v_and_b32_e32 v11, 0xffff0000, v5
	v_lshlrev_b32_e32 v12, 16, v6
	v_and_b32_e32 v13, 0xffff0000, v6
	v_lshlrev_b32_e32 v14, 16, v7
	v_and_b32_e32 v15, 0xffff0000, v7
	v_lshlrev_b32_e32 v52, 16, v32
	v_and_b32_e32 v53, 0xffff0000, v32
	v_lshlrev_b32_e32 v54, 16, v33
	v_and_b32_e32 v55, 0xffff0000, v33
	v_lshlrev_b32_e32 v56, 16, v34
	v_and_b32_e32 v57, 0xffff0000, v34
	v_lshlrev_b32_e32 v58, 16, v35
	v_and_b32_e32 v59, 0xffff0000, v35
	v_add_f32_e32 v8, v8, v52
	v_add_f32_e32 v9, v9, v53
	v_add_f32_e32 v10, v10, v54
	v_add_f32_e32 v11, v11, v55
	v_add_f32_e32 v12, v12, v56
	v_add_f32_e32 v13, v13, v57
	v_add_f32_e32 v14, v14, v58
	v_add_f32_e32 v15, v15, v59
	v_cvt_pk_bf16_f32 v32, v8, v9
	v_cvt_pk_bf16_f32 v33, v10, v11
	v_cvt_pk_bf16_f32 v34, v12, v13
	v_cvt_pk_bf16_f32 v35, v14, v15
	global_store_dwordx4 v63, v[32:35], s[100:101]
	s_add_u32 s100, s100, 0x8000
	s_addc_u32 s101, s101, 0
	ds_read_b128 v[4:7], v62 offset:17408
	s_waitcnt vmcnt(7) lgkmcnt(0)
	v_lshlrev_b32_e32 v8, 16, v4
	v_and_b32_e32 v9, 0xffff0000, v4
	v_lshlrev_b32_e32 v10, 16, v5
	v_and_b32_e32 v11, 0xffff0000, v5
	v_lshlrev_b32_e32 v12, 16, v6
	v_and_b32_e32 v13, 0xffff0000, v6
	v_lshlrev_b32_e32 v14, 16, v7
	v_and_b32_e32 v15, 0xffff0000, v7
	v_lshlrev_b32_e32 v52, 16, v36
	v_and_b32_e32 v53, 0xffff0000, v36
	v_lshlrev_b32_e32 v54, 16, v37
	v_and_b32_e32 v55, 0xffff0000, v37
	v_lshlrev_b32_e32 v56, 16, v38
	v_and_b32_e32 v57, 0xffff0000, v38
	v_lshlrev_b32_e32 v58, 16, v39
	v_and_b32_e32 v59, 0xffff0000, v39
	v_add_f32_e32 v8, v8, v52
	v_add_f32_e32 v9, v9, v53
	v_add_f32_e32 v10, v10, v54
	v_add_f32_e32 v11, v11, v55
	v_add_f32_e32 v12, v12, v56
	v_add_f32_e32 v13, v13, v57
	v_add_f32_e32 v14, v14, v58
	v_add_f32_e32 v15, v15, v59
	v_cvt_pk_bf16_f32 v36, v8, v9
	v_cvt_pk_bf16_f32 v37, v10, v11
	v_cvt_pk_bf16_f32 v38, v12, v13
	v_cvt_pk_bf16_f32 v39, v14, v15
	global_store_dwordx4 v63, v[36:39], s[100:101]
	s_add_u32 s100, s100, 0x8000
	s_addc_u32 s101, s101, 0
	ds_read_b128 v[4:7], v62 offset:21760
	s_waitcnt vmcnt(7) lgkmcnt(0)
	v_lshlrev_b32_e32 v8, 16, v4
	v_and_b32_e32 v9, 0xffff0000, v4
	v_lshlrev_b32_e32 v10, 16, v5
	v_and_b32_e32 v11, 0xffff0000, v5
	v_lshlrev_b32_e32 v12, 16, v6
	v_and_b32_e32 v13, 0xffff0000, v6
	v_lshlrev_b32_e32 v14, 16, v7
	v_and_b32_e32 v15, 0xffff0000, v7
	v_lshlrev_b32_e32 v52, 16, v40
	v_and_b32_e32 v53, 0xffff0000, v40
	v_lshlrev_b32_e32 v54, 16, v41
	v_and_b32_e32 v55, 0xffff0000, v41
	v_lshlrev_b32_e32 v56, 16, v42
	v_and_b32_e32 v57, 0xffff0000, v42
	v_lshlrev_b32_e32 v58, 16, v43
	v_and_b32_e32 v59, 0xffff0000, v43
	v_add_f32_e32 v8, v8, v52
	v_add_f32_e32 v9, v9, v53
	v_add_f32_e32 v10, v10, v54
	v_add_f32_e32 v11, v11, v55
	v_add_f32_e32 v12, v12, v56
	v_add_f32_e32 v13, v13, v57
	v_add_f32_e32 v14, v14, v58
	v_add_f32_e32 v15, v15, v59
	v_cvt_pk_bf16_f32 v40, v8, v9
	v_cvt_pk_bf16_f32 v41, v10, v11
	v_cvt_pk_bf16_f32 v42, v12, v13
	v_cvt_pk_bf16_f32 v43, v14, v15
	global_store_dwordx4 v63, v[40:43], s[100:101]
	s_add_u32 s100, s100, 0x8000
	s_addc_u32 s101, s101, 0
	ds_read_b128 v[4:7], v62 offset:26112
	s_waitcnt vmcnt(7) lgkmcnt(0)
	v_lshlrev_b32_e32 v8, 16, v4
	v_and_b32_e32 v9, 0xffff0000, v4
	v_lshlrev_b32_e32 v10, 16, v5
	v_and_b32_e32 v11, 0xffff0000, v5
	v_lshlrev_b32_e32 v12, 16, v6
	v_and_b32_e32 v13, 0xffff0000, v6
	v_lshlrev_b32_e32 v14, 16, v7
	v_and_b32_e32 v15, 0xffff0000, v7
	v_lshlrev_b32_e32 v52, 16, v44
	v_and_b32_e32 v53, 0xffff0000, v44
	v_lshlrev_b32_e32 v54, 16, v45
	v_and_b32_e32 v55, 0xffff0000, v45
	v_lshlrev_b32_e32 v56, 16, v46
	v_and_b32_e32 v57, 0xffff0000, v46
	v_lshlrev_b32_e32 v58, 16, v47
	v_and_b32_e32 v59, 0xffff0000, v47
	v_add_f32_e32 v8, v8, v52
	v_add_f32_e32 v9, v9, v53
	v_add_f32_e32 v10, v10, v54
	v_add_f32_e32 v11, v11, v55
	v_add_f32_e32 v12, v12, v56
	v_add_f32_e32 v13, v13, v57
	v_add_f32_e32 v14, v14, v58
	v_add_f32_e32 v15, v15, v59
	v_cvt_pk_bf16_f32 v44, v8, v9
	v_cvt_pk_bf16_f32 v45, v10, v11
	v_cvt_pk_bf16_f32 v46, v12, v13
	v_cvt_pk_bf16_f32 v47, v14, v15
	global_store_dwordx4 v63, v[44:47], s[100:101]
	s_add_u32 s100, s100, 0x8000
	s_addc_u32 s101, s101, 0
	ds_read_b128 v[4:7], v62 offset:30464
	s_waitcnt vmcnt(7) lgkmcnt(0)
	v_lshlrev_b32_e32 v8, 16, v4
	v_and_b32_e32 v9, 0xffff0000, v4
	v_lshlrev_b32_e32 v10, 16, v5
	v_and_b32_e32 v11, 0xffff0000, v5
	v_lshlrev_b32_e32 v12, 16, v6
	v_and_b32_e32 v13, 0xffff0000, v6
	v_lshlrev_b32_e32 v14, 16, v7
	v_and_b32_e32 v15, 0xffff0000, v7
	v_lshlrev_b32_e32 v52, 16, v48
	v_and_b32_e32 v53, 0xffff0000, v48
	v_lshlrev_b32_e32 v54, 16, v49
	v_and_b32_e32 v55, 0xffff0000, v49
	v_lshlrev_b32_e32 v56, 16, v50
	v_and_b32_e32 v57, 0xffff0000, v50
	v_lshlrev_b32_e32 v58, 16, v51
	v_and_b32_e32 v59, 0xffff0000, v51
	v_add_f32_e32 v8, v8, v52
	v_add_f32_e32 v9, v9, v53
	v_add_f32_e32 v10, v10, v54
	v_add_f32_e32 v11, v11, v55
	v_add_f32_e32 v12, v12, v56
	v_add_f32_e32 v13, v13, v57
	v_add_f32_e32 v14, v14, v58
	v_add_f32_e32 v15, v15, v59
	v_cvt_pk_bf16_f32 v48, v8, v9
	v_cvt_pk_bf16_f32 v49, v10, v11
	v_cvt_pk_bf16_f32 v50, v12, v13
	v_cvt_pk_bf16_f32 v51, v14, v15
	global_store_dwordx4 v63, v[48:51], s[100:101]
	s_branch .LBB0_956

; DEV int tid_() { int t = threadIdx.x; asm volatile("" : "+v"(t)); return t; }
; DEV int bid_() { int b = blockIdx.x; asm volatile("" : "+s"(b)); return b; }
; template <int NI, bool DEEP = true>
; DEV void gemm_tile(f32x16 (&acc)[2][NI], const bf16* __restrict__ A, int lda, const bf16* __restrict__ Bt, int ldb,
;                    int K, bf16* sA, bf16* sB) {
;   int tid = tid_(), lane = tid & 63, wave = tid >> 6;
;   int wm = wave >> 1, wn = wave & 1;
;   int lr = tid >> 3, lc = (tid & 7) * 8;
;   const bf16* Ap = A + (size_t)lr * lda + lc;
;   const bf16* Bp = Bt + (size_t)lr * ldb + lc;
;   u32x4 ra0[4], rb0[2 * NI], ra1[4], rb1[2 * NI];
;     ...
;   G_LOAD(ra0, rb0, 0)
;   if (DEEP) {
;     if (64 < K) G_LOAD(ra1, rb1, 64)
;     for (int k0 = 0; k0 < K; k0 += 128) {
;       G_STEP(ra0, rb0, k0 + 128)
;       if (k0 + 64 < K) G_STEP(ra1, rb1, k0 + 192)
;     }
;   } else {
;     for (int k0 = 0; k0 < K; k0 += 64) G_STEP(ra0, rb0, k0 + 64)
;   }
; __device__ void phase_out(PRef p, int l, const bf16* M, const float* xl, const float* xc, bf16* sA, bf16* sB) {
;     ...
;   for (int t = bid_() >> 3; t < 36 * 8; t += per_) {
;     int rt = xcd_ + 8 * (t / 8), ct = t % 8;
;     if (skip_rt(l, rt)) continue;
;     f32x16 acc[2][2];
;     zero_acc<2>(acc);
;     gemm_tile<2>(acc, M + (size_t)rt * 128 * 1024, 1024, p.WOUT + (size_t)ct * 128 * 1024, 1024, 1024, sA, sB);
.Lout_ptr:
	s_add_u32 s14, s14, s15
	s_lshl_b32 s16, s14, 12
	s_lshl_b32 s14, s20, 9
	s_add_u32 s16, s16, s14
	s_add_u32 s30, s30, s16
	s_addc_u32 s31, s31, 0
	s_add_u32 s26, s26, s16
	s_addc_u32 s27, s27, 0
	v_lshrrev_b32_e32 v242, 4, v196
	v_and_b32_e32 v243, 15, v196
	v_lshlrev_b32_e32 v242, 12, v242
	v_lshl_add_u32 v242, v243, 5, v242
	v_and_b32_e32 v0, 63, v196
	v_lshrrev_b32_e32 v1, 6, v196
	v_lshrrev_b32_e32 v2, 3, v0
	v_readfirstlane_b32 s16, v1
	v_lshrrev_b32_e32 v78, 1, v2
	v_and_b32_e32 v79, 7, v0
	v_xor_b32_e32 v78, v79, v78
	v_lshlrev_b32_e32 v78, 4, v78
	v_lshl_or_b32 v68, v2, 11, v78
	v_xor_b32_e32 v69, 64, v68
	v_lshrrev_b32_e32 v78, 5, v0
	v_bfe_u32 v79, v0, 1, 3
	v_and_b32_e32 v2, 31, v0
	v_lshrrev_b32_e32 v0, 1, v1
	v_and_b32_e32 v1, 1, v1
	v_lshl_add_u32 v0, v0, 6, v2
	v_lshl_add_u32 v1, v1, 6, v2
	v_lshlrev_b32_e32 v0, 7, v0
	v_lshlrev_b32_e32 v1, 7, v1
	v_add_u32_e32 v1, 0x4000, v1
	v_add_u32_e32 v2, 0, v78
	v_xor_b32_e32 v2, v2, v79
	v_lshl_add_u32 v70, v2, 4, v0
	v_lshl_add_u32 v74, v2, 4, v1
	v_add_u32_e32 v2, 2, v78
	v_xor_b32_e32 v2, v2, v79
	v_lshl_add_u32 v71, v2, 4, v0
	v_lshl_add_u32 v75, v2, 4, v1
	v_add_u32_e32 v2, 4, v78
	v_xor_b32_e32 v2, v2, v79
	v_lshl_add_u32 v72, v2, 4, v0
	v_lshl_add_u32 v76, v2, 4, v1
	v_add_u32_e32 v2, 6, v78
	v_xor_b32_e32 v2, v2, v79
	v_lshl_add_u32 v73, v2, 4, v0
	v_lshl_add_u32 v77, v2, 4, v1
	s_lshl_b32 s17, s16, 16
	s_lshl_b32 s16, s16, 12
	s_add_u32 s98, s98, s17
	s_addc_u32 s99, s99, 0
	s_add_u32 s100, s100, s17
	s_addc_u32 s101, s101, 0
	s_waitcnt lgkmcnt(0)
	s_barrier
	s_add_u32 m0, s16, 0x0
	s_nop 0
	global_load_lds_dwordx4 v68, s[98:99]
	s_add_u32 m0, s16, 0x400
	s_add_u32 s14, s98, 0x4000
	s_addc_u32 s15, s99, 0
	global_load_lds_dwordx4 v69, s[14:15]
	s_add_u32 m0, s16, 0x800
	s_add_u32 s14, s98, 0x8000
	s_addc_u32 s15, s99, 0
	global_load_lds_dwordx4 v68, s[14:15]
	s_add_u32 m0, s16, 0xc00
	s_add_u32 s14, s98, 0xc000
	s_addc_u32 s15, s99, 0
	global_load_lds_dwordx4 v69, s[14:15]
	s_add_u32 m0, s16, 0x4000
	s_nop 0
	global_load_lds_dwordx4 v68, s[100:101]
	s_add_u32 m0, s16, 0x4400
	s_add_u32 s14, s100, 0x4000
	s_addc_u32 s15, s101, 0
	global_load_lds_dwordx4 v69, s[14:15]
	s_add_u32 m0, s16, 0x4800
	s_add_u32 s14, s100, 0x8000
	s_addc_u32 s15, s101, 0
	global_load_lds_dwordx4 v68, s[14:15]
	s_add_u32 m0, s16, 0x4c00
	s_add_u32 s14, s100, 0xc000
	s_addc_u32 s15, s101, 0
	global_load_lds_dwordx4 v69, s[14:15]
	s_add_u32 s98, s98, 0x80
	s_addc_u32 s99, s99, 0
	s_add_u32 s100, s100, 0x80
	s_addc_u32 s101, s101, 0
	v_mov_b32_e32 v4, 0
	v_mov_b32_e32 v5, 0
	v_mov_b32_e32 v6, 0
	v_mov_b32_e32 v7, 0
	v_mov_b32_e32 v8, 0
	v_mov_b32_e32 v9, 0
	v_mov_b32_e32 v10, 0
	v_mov_b32_e32 v11, 0
	v_mov_b32_e32 v12, 0
	v_mov_b32_e32 v13, 0
	v_mov_b32_e32 v14, 0
	v_mov_b32_e32 v15, 0
	v_mov_b32_e32 v16, 0
	v_mov_b32_e32 v17, 0
	v_mov_b32_e32 v18, 0
	v_mov_b32_e32 v19, 0
	v_mov_b32_e32 v20, 0
	v_mov_b32_e32 v21, 0
	v_mov_b32_e32 v22, 0
	v_mov_b32_e32 v23, 0
	v_mov_b32_e32 v24, 0
	v_mov_b32_e32 v25, 0
	v_mov_b32_e32 v26, 0
	v_mov_b32_e32 v27, 0
	v_mov_b32_e32 v28, 0
	v_mov_b32_e32 v29, 0
	v_mov_b32_e32 v30, 0
	v_mov_b32_e32 v31, 0
	v_mov_b32_e32 v32, 0
	v_mov_b32_e32 v33, 0
	v_mov_b32_e32 v34, 0
	v_mov_b32_e32 v35, 0
	v_mov_b32_e32 v36, 0
	v_mov_b32_e32 v37, 0
	v_mov_b32_e32 v38, 0
	v_mov_b32_e32 v39, 0
	v_mov_b32_e32 v40, 0
	v_mov_b32_e32 v41, 0
	v_mov_b32_e32 v42, 0
	v_mov_b32_e32 v43, 0
	v_mov_b32_e32 v44, 0
	v_mov_b32_e32 v45, 0
	v_mov_b32_e32 v46, 0
	v_mov_b32_e32 v47, 0
	v_mov_b32_e32 v48, 0
	v_mov_b32_e32 v49, 0
	v_mov_b32_e32 v50, 0
	v_mov_b32_e32 v51, 0
	v_mov_b32_e32 v52, 0
	v_mov_b32_e32 v53, 0
	v_mov_b32_e32 v54, 0
	v_mov_b32_e32 v55, 0
	v_mov_b32_e32 v56, 0
	v_mov_b32_e32 v57, 0
	v_mov_b32_e32 v58, 0
	v_mov_b32_e32 v59, 0
	v_mov_b32_e32 v60, 0
	v_mov_b32_e32 v61, 0
	v_mov_b32_e32 v62, 0
	v_mov_b32_e32 v63, 0
	v_mov_b32_e32 v64, 0
	v_mov_b32_e32 v65, 0
	v_mov_b32_e32 v66, 0
	v_mov_b32_e32 v67, 0
	s_waitcnt vmcnt(0)
	s_barrier
	ds_read_b128 v[88:91], v74 offset:0
	ds_read_b128 v[80:83], v70 offset:0
	ds_read_b128 v[84:87], v70 offset:4096
	ds_read_b128 v[92:95], v74 offset:4096
	s_waitcnt lgkmcnt(2)
	v_mfma_f32_32x32x16_bf16 v[52:67], v[88:91], v[80:83], v[52:67]
	s_add_u32 m0, s16, 0x8000
	s_nop 0
	global_load_lds_dwordx4 v68, s[98:99]
	ds_read_b128 v[104:107], v75 offset:0
	ds_read_b128 v[96:99], v71 offset:0
	s_waitcnt lgkmcnt(3)
	v_mfma_f32_32x32x16_bf16 v[20:35], v[88:91], v[84:87], v[20:35]
	s_add_u32 m0, s16, 0x8400
	s_add_u32 s14, s98, 0x4000
	s_addc_u32 s15, s99, 0
	global_load_lds_dwordx4 v69, s[14:15]
	ds_read_b128 v[100:103], v71 offset:4096
	s_waitcnt lgkmcnt(3)
	v_mfma_f32_32x32x16_bf16 v[36:51], v[92:95], v[80:83], v[36:51]
	s_add_u32 m0, s16, 0x8800
	s_add_u32 s14, s98, 0x8000
	s_addc_u32 s15, s99, 0
	global_load_lds_dwordx4 v68, s[14:15]
	ds_read_b128 v[108:111], v75 offset:4096
	v_mfma_f32_32x32x16_bf16 v[4:19], v[92:95], v[84:87], v[4:19]
	s_add_u32 m0, s16, 0x8c00
	s_add_u32 s14, s98, 0xc000
	s_addc_u32 s15, s99, 0
	global_load_lds_dwordx4 v69, s[14:15]
	s_waitcnt lgkmcnt(2)
	v_mfma_f32_32x32x16_bf16 v[52:67], v[104:107], v[96:99], v[52:67]
	s_add_u32 m0, s16, 0xd840
	s_nop 0
	global_load_lds_dwordx4 v68, s[100:101]
	ds_read_b128 v[120:123], v76 offset:0
	ds_read_b128 v[112:115], v72 offset:0
	s_waitcnt lgkmcnt(3)
	v_mfma_f32_32x32x16_bf16 v[20:35], v[104:107], v[100:103], v[20:35]
	s_add_u32 m0, s16, 0xdc40
	s_add_u32 s14, s100, 0x4000
	s_addc_u32 s15, s101, 0
	global_load_lds_dwordx4 v69, s[14:15]
	ds_read_b128 v[116:119], v72 offset:4096
	s_waitcnt lgkmcnt(3)
	v_mfma_f32_32x32x16_bf16 v[36:51], v[108:111], v[96:99], v[36:51]
	s_add_u32 m0, s16, 0xe040
	s_add_u32 s14, s100, 0x8000
	s_addc_u32 s15, s101, 0
	global_load_lds_dwordx4 v68, s[14:15]
	ds_read_b128 v[124:127], v76 offset:4096
	v_mfma_f32_32x32x16_bf16 v[4:19], v[108:111], v[100:103], v[4:19]
	s_add_u32 m0, s16, 0xe440
	s_add_u32 s14, s100, 0xc000
	s_addc_u32 s15, s101, 0
	global_load_lds_dwordx4 v69, s[14:15]
	s_waitcnt lgkmcnt(2)
	v_mfma_f32_32x32x16_bf16 v[52:67], v[120:123], v[112:115], v[52:67]
	s_add_u32 s98, s98, 0x80
	s_addc_u32 s99, s99, 0
	s_add_u32 s100, s100, 0x80
	s_addc_u32 s101, s101, 0
	ds_read_b128 v[88:91], v77 offset:0
	ds_read_b128 v[80:83], v73 offset:0
	s_waitcnt lgkmcnt(3)
	v_mfma_f32_32x32x16_bf16 v[20:35], v[120:123], v[116:119], v[20:35]
	global_load_dwordx4 v[162:165], v242, s[30:31]
	ds_read_b128 v[84:87], v73 offset:4096
	s_waitcnt lgkmcnt(3)
	v_mfma_f32_32x32x16_bf16 v[36:51], v[124:127], v[112:115], v[36:51]
	ds_read_b128 v[92:95], v77 offset:4096
	v_mfma_f32_32x32x16_bf16 v[4:19], v[124:127], v[116:119], v[4:19]
	s_waitcnt lgkmcnt(2)
	v_mfma_f32_32x32x16_bf16 v[52:67], v[88:91], v[80:83], v[52:67]
	s_waitcnt lgkmcnt(1)
	v_mfma_f32_32x32x16_bf16 v[20:35], v[88:91], v[84:87], v[20:35]
	s_waitcnt lgkmcnt(0)
	v_mfma_f32_32x32x16_bf16 v[36:51], v[92:95], v[80:83], v[36:51]
	v_mfma_f32_32x32x16_bf16 v[4:19], v[92:95], v[84:87], v[4:19]
	s_waitcnt vmcnt(1)
	s_barrier
; template <int NI, bool DEEP = true>
; DEV void gemm_tile(f32x16 (&acc)[2][NI], const bf16* __restrict__ A, int lda, const bf16* __restrict__ Bt, int ldb,
;                    int K, bf16* sA, bf16* sB) {
;     ...
;   G_LOAD(ra0, rb0, 0)
;   if (DEEP) {
;     if (64 < K) G_LOAD(ra1, rb1, 64)
;     for (int k0 = 0; k0 < K; k0 += 128) {
;       G_STEP(ra0, rb0, k0 + 128)
;       if (k0 + 64 < K) G_STEP(ra1, rb1, k0 + 192)
;     }
	ds_read_b128 v[88:91], v74 offset:38976
	ds_read_b128 v[80:83], v70 offset:32768
	ds_read_b128 v[84:87], v70 offset:36864
	ds_read_b128 v[92:95], v74 offset:43072
	s_waitcnt lgkmcnt(2)
	v_mfma_f32_32x32x16_bf16 v[52:67], v[88:91], v[80:83], v[52:67]
	s_add_u32 m0, s16, 0x0
	s_nop 0
	global_load_lds_dwordx4 v68, s[98:99]
	ds_read_b128 v[104:107], v75 offset:38976
	ds_read_b128 v[96:99], v71 offset:32768
	s_waitcnt lgkmcnt(3)
	v_mfma_f32_32x32x16_bf16 v[20:35], v[88:91], v[84:87], v[20:35]
	s_add_u32 m0, s16, 0x400
	s_add_u32 s14, s98, 0x4000
	s_addc_u32 s15, s99, 0
	global_load_lds_dwordx4 v69, s[14:15]
	ds_read_b128 v[100:103], v71 offset:36864
	s_waitcnt lgkmcnt(3)
	v_mfma_f32_32x32x16_bf16 v[36:51], v[92:95], v[80:83], v[36:51]
	s_add_u32 m0, s16, 0x800
	s_add_u32 s14, s98, 0x8000
	s_addc_u32 s15, s99, 0
	global_load_lds_dwordx4 v68, s[14:15]
	ds_read_b128 v[108:111], v75 offset:43072
	v_mfma_f32_32x32x16_bf16 v[4:19], v[92:95], v[84:87], v[4:19]
	s_add_u32 m0, s16, 0xc00
	s_add_u32 s14, s98, 0xc000
	s_addc_u32 s15, s99, 0
	global_load_lds_dwordx4 v69, s[14:15]
	s_waitcnt lgkmcnt(2)
	v_mfma_f32_32x32x16_bf16 v[52:67], v[104:107], v[96:99], v[52:67]
	s_add_u32 m0, s16, 0x4000
	s_nop 0
	global_load_lds_dwordx4 v68, s[100:101]
	ds_read_b128 v[120:123], v76 offset:38976
	ds_read_b128 v[112:115], v72 offset:32768
	s_waitcnt lgkmcnt(3)
	v_mfma_f32_32x32x16_bf16 v[20:35], v[104:107], v[100:103], v[20:35]
	s_add_u32 m0, s16, 0x4400
	s_add_u32 s14, s100, 0x4000
	s_addc_u32 s15, s101, 0
	global_load_lds_dwordx4 v69, s[14:15]
	ds_read_b128 v[116:119], v72 offset:36864
	s_waitcnt lgkmcnt(3)
	v_mfma_f32_32x32x16_bf16 v[36:51], v[108:111], v[96:99], v[36:51]
	s_add_u32 m0, s16, 0x4800
	s_add_u32 s14, s100, 0x8000
	s_addc_u32 s15, s101, 0
	global_load_lds_dwordx4 v68, s[14:15]
	ds_read_b128 v[124:127], v76 offset:43072
	v_mfma_f32_32x32x16_bf16 v[4:19], v[108:111], v[100:103], v[4:19]
	s_add_u32 m0, s16, 0x4c00
	s_add_u32 s14, s100, 0xc000
	s_addc_u32 s15, s101, 0
	global_load_lds_dwordx4 v69, s[14:15]
	s_waitcnt lgkmcnt(2)
	v_mfma_f32_32x32x16_bf16 v[52:67], v[120:123], v[112:115], v[52:67]
	s_add_u32 s98, s98, 0x80
	s_addc_u32 s99, s99, 0
	s_add_u32 s100, s100, 0x80
	s_addc_u32 s101, s101, 0
	ds_read_b128 v[88:91], v77 offset:38976
	ds_read_b128 v[80:83], v73 offset:32768
	s_waitcnt lgkmcnt(3)
	v_mfma_f32_32x32x16_bf16 v[20:35], v[120:123], v[116:119], v[20:35]
	global_load_dwordx4 v[166:169], v242, s[30:31] offset:16
	s_add_u32 s30, s30, 0x10000
	s_addc_u32 s31, s31, 0
	ds_read_b128 v[84:87], v73 offset:36864
	s_waitcnt lgkmcnt(3)
	v_mfma_f32_32x32x16_bf16 v[36:51], v[124:127], v[112:115], v[36:51]
	ds_read_b128 v[92:95], v77 offset:43072
	v_mfma_f32_32x32x16_bf16 v[4:19], v[124:127], v[116:119], v[4:19]
	s_waitcnt lgkmcnt(2)
	v_mfma_f32_32x32x16_bf16 v[52:67], v[88:91], v[80:83], v[52:67]
	s_waitcnt lgkmcnt(1)
	v_mfma_f32_32x32x16_bf16 v[20:35], v[88:91], v[84:87], v[20:35]
	s_waitcnt lgkmcnt(0)
	v_mfma_f32_32x32x16_bf16 v[36:51], v[92:95], v[80:83], v[36:51]
	v_mfma_f32_32x32x16_bf16 v[4:19], v[92:95], v[84:87], v[4:19]
	s_waitcnt vmcnt(1)
	s_barrier
	ds_read_b128 v[88:91], v74 offset:0
	ds_read_b128 v[80:83], v70 offset:0
	ds_read_b128 v[84:87], v70 offset:4096
	ds_read_b128 v[92:95], v74 offset:4096
	s_waitcnt lgkmcnt(2)
	v_mfma_f32_32x32x16_bf16 v[52:67], v[88:91], v[80:83], v[52:67]
	s_add_u32 m0, s16, 0x8000
	s_nop 0
	global_load_lds_dwordx4 v68, s[98:99]
	ds_read_b128 v[104:107], v75 offset:0
	ds_read_b128 v[96:99], v71 offset:0
	s_waitcnt lgkmcnt(3)
	v_mfma_f32_32x32x16_bf16 v[20:35], v[88:91], v[84:87], v[20:35]
	s_add_u32 m0, s16, 0x8400
	s_add_u32 s14, s98, 0x4000
	s_addc_u32 s15, s99, 0
	global_load_lds_dwordx4 v69, s[14:15]
	ds_read_b128 v[100:103], v71 offset:4096
	s_waitcnt lgkmcnt(3)
	v_mfma_f32_32x32x16_bf16 v[36:51], v[92:95], v[80:83], v[36:51]
	s_add_u32 m0, s16, 0x8800
	s_add_u32 s14, s98, 0x8000
	s_addc_u32 s15, s99, 0
	global_load_lds_dwordx4 v68, s[14:15]
	ds_read_b128 v[108:111], v75 offset:4096
	v_mfma_f32_32x32x16_bf16 v[4:19], v[92:95], v[84:87], v[4:19]
	s_add_u32 m0, s16, 0x8c00
	s_add_u32 s14, s98, 0xc000
	s_addc_u32 s15, s99, 0
	global_load_lds_dwordx4 v69, s[14:15]
	s_waitcnt lgkmcnt(2)
	v_mfma_f32_32x32x16_bf16 v[52:67], v[104:107], v[96:99], v[52:67]
	s_add_u32 m0, s16, 0xd840
	s_nop 0
	global_load_lds_dwordx4 v68, s[100:101]
	ds_read_b128 v[120:123], v76 offset:0
	ds_read_b128 v[112:115], v72 offset:0
	s_waitcnt lgkmcnt(3)
	v_mfma_f32_32x32x16_bf16 v[20:35], v[104:107], v[100:103], v[20:35]
	s_add_u32 m0, s16, 0xdc40
	s_add_u32 s14, s100, 0x4000
	s_addc_u32 s15, s101, 0
	global_load_lds_dwordx4 v69, s[14:15]
	ds_read_b128 v[116:119], v72 offset:4096
	s_waitcnt lgkmcnt(3)
	v_mfma_f32_32x32x16_bf16 v[36:51], v[108:111], v[96:99], v[36:51]
	s_add_u32 m0, s16, 0xe040
	s_add_u32 s14, s100, 0x8000
	s_addc_u32 s15, s101, 0
	global_load_lds_dwordx4 v68, s[14:15]
	ds_read_b128 v[124:127], v76 offset:4096
	v_mfma_f32_32x32x16_bf16 v[4:19], v[108:111], v[100:103], v[4:19]
	s_add_u32 m0, s16, 0xe440
	s_add_u32 s14, s100, 0xc000
	s_addc_u32 s15, s101, 0
	global_load_lds_dwordx4 v69, s[14:15]
	s_waitcnt lgkmcnt(2)
	v_mfma_f32_32x32x16_bf16 v[52:67], v[120:123], v[112:115], v[52:67]
	s_add_u32 s98, s98, 0x80
	s_addc_u32 s99, s99, 0
	s_add_u32 s100, s100, 0x80
	s_addc_u32 s101, s101, 0
	ds_read_b128 v[88:91], v77 offset:0
	ds_read_b128 v[80:83], v73 offset:0
	s_waitcnt lgkmcnt(3)
	v_mfma_f32_32x32x16_bf16 v[20:35], v[120:123], v[116:119], v[20:35]
	global_load_dwordx4 v[170:173], v242, s[30:31]
	ds_read_b128 v[84:87], v73 offset:4096
	s_waitcnt lgkmcnt(3)
	v_mfma_f32_32x32x16_bf16 v[36:51], v[124:127], v[112:115], v[36:51]
	ds_read_b128 v[92:95], v77 offset:4096
	v_mfma_f32_32x32x16_bf16 v[4:19], v[124:127], v[116:119], v[4:19]
	s_waitcnt lgkmcnt(2)
	v_mfma_f32_32x32x16_bf16 v[52:67], v[88:91], v[80:83], v[52:67]
	s_waitcnt lgkmcnt(1)
	v_mfma_f32_32x32x16_bf16 v[20:35], v[88:91], v[84:87], v[20:35]
	s_waitcnt lgkmcnt(0)
	v_mfma_f32_32x32x16_bf16 v[36:51], v[92:95], v[80:83], v[36:51]
	v_mfma_f32_32x32x16_bf16 v[4:19], v[92:95], v[84:87], v[4:19]
	s_waitcnt vmcnt(1)
	s_barrier
; template <int NI, bool DEEP = true>
; DEV void gemm_tile(f32x16 (&acc)[2][NI], const bf16* __restrict__ A, int lda, const bf16* __restrict__ Bt, int ldb,
;                    int K, bf16* sA, bf16* sB) {
;     ...
;   G_LOAD(ra0, rb0, 0)
;   if (DEEP) {
;     if (64 < K) G_LOAD(ra1, rb1, 64)
;     for (int k0 = 0; k0 < K; k0 += 128) {
;       G_STEP(ra0, rb0, k0 + 128)
;       if (k0 + 64 < K) G_STEP(ra1, rb1, k0 + 192)
;     }
	ds_read_b128 v[88:91], v74 offset:38976
	ds_read_b128 v[80:83], v70 offset:32768
	ds_read_b128 v[84:87], v70 offset:36864
	ds_read_b128 v[92:95], v74 offset:43072
	s_waitcnt lgkmcnt(2)
	v_mfma_f32_32x32x16_bf16 v[52:67], v[88:91], v[80:83], v[52:67]
	s_add_u32 m0, s16, 0x0
	s_nop 0
	global_load_lds_dwordx4 v68, s[98:99]
	ds_read_b128 v[104:107], v75 offset:38976
	ds_read_b128 v[96:99], v71 offset:32768
	s_waitcnt lgkmcnt(3)
	v_mfma_f32_32x32x16_bf16 v[20:35], v[88:91], v[84:87], v[20:35]
	s_add_u32 m0, s16, 0x400
	s_add_u32 s14, s98, 0x4000
	s_addc_u32 s15, s99, 0
	global_load_lds_dwordx4 v69, s[14:15]
	ds_read_b128 v[100:103], v71 offset:36864
	s_waitcnt lgkmcnt(3)
	v_mfma_f32_32x32x16_bf16 v[36:51], v[92:95], v[80:83], v[36:51]
	s_add_u32 m0, s16, 0x800
	s_add_u32 s14, s98, 0x8000
	s_addc_u32 s15, s99, 0
	global_load_lds_dwordx4 v68, s[14:15]
	ds_read_b128 v[108:111], v75 offset:43072
	v_mfma_f32_32x32x16_bf16 v[4:19], v[92:95], v[84:87], v[4:19]
	s_add_u32 m0, s16, 0xc00
	s_add_u32 s14, s98, 0xc000
	s_addc_u32 s15, s99, 0
	global_load_lds_dwordx4 v69, s[14:15]
	s_waitcnt lgkmcnt(2)
	v_mfma_f32_32x32x16_bf16 v[52:67], v[104:107], v[96:99], v[52:67]
	s_add_u32 m0, s16, 0x4000
	s_nop 0
	global_load_lds_dwordx4 v68, s[100:101]
	ds_read_b128 v[120:123], v76 offset:38976
	ds_read_b128 v[112:115], v72 offset:32768
	s_waitcnt lgkmcnt(3)
	v_mfma_f32_32x32x16_bf16 v[20:35], v[104:107], v[100:103], v[20:35]
	s_add_u32 m0, s16, 0x4400
	s_add_u32 s14, s100, 0x4000
	s_addc_u32 s15, s101, 0
	global_load_lds_dwordx4 v69, s[14:15]
	ds_read_b128 v[116:119], v72 offset:36864
	s_waitcnt lgkmcnt(3)
	v_mfma_f32_32x32x16_bf16 v[36:51], v[108:111], v[96:99], v[36:51]
	s_add_u32 m0, s16, 0x4800
	s_add_u32 s14, s100, 0x8000
	s_addc_u32 s15, s101, 0
	global_load_lds_dwordx4 v68, s[14:15]
	ds_read_b128 v[124:127], v76 offset:43072
	v_mfma_f32_32x32x16_bf16 v[4:19], v[108:111], v[100:103], v[4:19]
	s_add_u32 m0, s16, 0x4c00
	s_add_u32 s14, s100, 0xc000
	s_addc_u32 s15, s101, 0
	global_load_lds_dwordx4 v69, s[14:15]
	s_waitcnt lgkmcnt(2)
	v_mfma_f32_32x32x16_bf16 v[52:67], v[120:123], v[112:115], v[52:67]
	s_add_u32 s98, s98, 0x80
	s_addc_u32 s99, s99, 0
	s_add_u32 s100, s100, 0x80
	s_addc_u32 s101, s101, 0
	ds_read_b128 v[88:91], v77 offset:38976
	ds_read_b128 v[80:83], v73 offset:32768
	s_waitcnt lgkmcnt(3)
	v_mfma_f32_32x32x16_bf16 v[20:35], v[120:123], v[116:119], v[20:35]
	global_load_dwordx4 v[174:177], v242, s[30:31] offset:16
	s_add_u32 s30, s30, 0x10000
	s_addc_u32 s31, s31, 0
	ds_read_b128 v[84:87], v73 offset:36864
	s_waitcnt lgkmcnt(3)
	v_mfma_f32_32x32x16_bf16 v[36:51], v[124:127], v[112:115], v[36:51]
	ds_read_b128 v[92:95], v77 offset:43072
	v_mfma_f32_32x32x16_bf16 v[4:19], v[124:127], v[116:119], v[4:19]
	s_waitcnt lgkmcnt(2)
	v_mfma_f32_32x32x16_bf16 v[52:67], v[88:91], v[80:83], v[52:67]
	s_waitcnt lgkmcnt(1)
	v_mfma_f32_32x32x16_bf16 v[20:35], v[88:91], v[84:87], v[20:35]
	s_waitcnt lgkmcnt(0)
	v_mfma_f32_32x32x16_bf16 v[36:51], v[92:95], v[80:83], v[36:51]
	v_mfma_f32_32x32x16_bf16 v[4:19], v[92:95], v[84:87], v[4:19]
	s_waitcnt vmcnt(1)
	s_barrier
	ds_read_b128 v[88:91], v74 offset:0
	ds_read_b128 v[80:83], v70 offset:0
	ds_read_b128 v[84:87], v70 offset:4096
	ds_read_b128 v[92:95], v74 offset:4096
	s_waitcnt lgkmcnt(2)
	v_mfma_f32_32x32x16_bf16 v[52:67], v[88:91], v[80:83], v[52:67]
	s_add_u32 m0, s16, 0x8000
	s_nop 0
	global_load_lds_dwordx4 v68, s[98:99]
	ds_read_b128 v[104:107], v75 offset:0
	ds_read_b128 v[96:99], v71 offset:0
	s_waitcnt lgkmcnt(3)
	v_mfma_f32_32x32x16_bf16 v[20:35], v[88:91], v[84:87], v[20:35]
	s_add_u32 m0, s16, 0x8400
	s_add_u32 s14, s98, 0x4000
	s_addc_u32 s15, s99, 0
	global_load_lds_dwordx4 v69, s[14:15]
	ds_read_b128 v[100:103], v71 offset:4096
	s_waitcnt lgkmcnt(3)
	v_mfma_f32_32x32x16_bf16 v[36:51], v[92:95], v[80:83], v[36:51]
	s_add_u32 m0, s16, 0x8800
	s_add_u32 s14, s98, 0x8000
	s_addc_u32 s15, s99, 0
	global_load_lds_dwordx4 v68, s[14:15]
	ds_read_b128 v[108:111], v75 offset:4096
	v_mfma_f32_32x32x16_bf16 v[4:19], v[92:95], v[84:87], v[4:19]
	s_add_u32 m0, s16, 0x8c00
	s_add_u32 s14, s98, 0xc000
	s_addc_u32 s15, s99, 0
	global_load_lds_dwordx4 v69, s[14:15]
	s_waitcnt lgkmcnt(2)
	v_mfma_f32_32x32x16_bf16 v[52:67], v[104:107], v[96:99], v[52:67]
	s_add_u32 m0, s16, 0xd840
	s_nop 0
	global_load_lds_dwordx4 v68, s[100:101]
	ds_read_b128 v[120:123], v76 offset:0
	ds_read_b128 v[112:115], v72 offset:0
	s_waitcnt lgkmcnt(3)
	v_mfma_f32_32x32x16_bf16 v[20:35], v[104:107], v[100:103], v[20:35]
	s_add_u32 m0, s16, 0xdc40
	s_add_u32 s14, s100, 0x4000
	s_addc_u32 s15, s101, 0
	global_load_lds_dwordx4 v69, s[14:15]
	ds_read_b128 v[116:119], v72 offset:4096
	s_waitcnt lgkmcnt(3)
	v_mfma_f32_32x32x16_bf16 v[36:51], v[108:111], v[96:99], v[36:51]
	s_add_u32 m0, s16, 0xe040
	s_add_u32 s14, s100, 0x8000
	s_addc_u32 s15, s101, 0
	global_load_lds_dwordx4 v68, s[14:15]
	ds_read_b128 v[124:127], v76 offset:4096
	v_mfma_f32_32x32x16_bf16 v[4:19], v[108:111], v[100:103], v[4:19]
	s_add_u32 m0, s16, 0xe440
	s_add_u32 s14, s100, 0xc000
	s_addc_u32 s15, s101, 0
	global_load_lds_dwordx4 v69, s[14:15]
	s_waitcnt lgkmcnt(2)
	v_mfma_f32_32x32x16_bf16 v[52:67], v[120:123], v[112:115], v[52:67]
	s_add_u32 s98, s98, 0x80
	s_addc_u32 s99, s99, 0
	s_add_u32 s100, s100, 0x80
	s_addc_u32 s101, s101, 0
	ds_read_b128 v[88:91], v77 offset:0
	ds_read_b128 v[80:83], v73 offset:0
	s_waitcnt lgkmcnt(3)
	v_mfma_f32_32x32x16_bf16 v[20:35], v[120:123], v[116:119], v[20:35]
	global_load_dwordx4 v[178:181], v242, s[30:31]
	ds_read_b128 v[84:87], v73 offset:4096
	s_waitcnt lgkmcnt(3)
	v_mfma_f32_32x32x16_bf16 v[36:51], v[124:127], v[112:115], v[36:51]
	ds_read_b128 v[92:95], v77 offset:4096
	v_mfma_f32_32x32x16_bf16 v[4:19], v[124:127], v[116:119], v[4:19]
	s_waitcnt lgkmcnt(2)
	v_mfma_f32_32x32x16_bf16 v[52:67], v[88:91], v[80:83], v[52:67]
	s_waitcnt lgkmcnt(1)
	v_mfma_f32_32x32x16_bf16 v[20:35], v[88:91], v[84:87], v[20:35]
	s_waitcnt lgkmcnt(0)
	v_mfma_f32_32x32x16_bf16 v[36:51], v[92:95], v[80:83], v[36:51]
	v_mfma_f32_32x32x16_bf16 v[4:19], v[92:95], v[84:87], v[4:19]
	s_waitcnt vmcnt(1)
	s_barrier
; template <int NI, bool DEEP = true>
; DEV void gemm_tile(f32x16 (&acc)[2][NI], const bf16* __restrict__ A, int lda, const bf16* __restrict__ Bt, int ldb,
;                    int K, bf16* sA, bf16* sB) {
;     ...
;   G_LOAD(ra0, rb0, 0)
;   if (DEEP) {
;     if (64 < K) G_LOAD(ra1, rb1, 64)
;     for (int k0 = 0; k0 < K; k0 += 128) {
;       G_STEP(ra0, rb0, k0 + 128)
;       if (k0 + 64 < K) G_STEP(ra1, rb1, k0 + 192)
;     }
	ds_read_b128 v[88:91], v74 offset:38976
	ds_read_b128 v[80:83], v70 offset:32768
	ds_read_b128 v[84:87], v70 offset:36864
	ds_read_b128 v[92:95], v74 offset:43072
	s_waitcnt lgkmcnt(2)
	v_mfma_f32_32x32x16_bf16 v[52:67], v[88:91], v[80:83], v[52:67]
	s_add_u32 m0, s16, 0x0
	s_nop 0
	global_load_lds_dwordx4 v68, s[98:99]
	ds_read_b128 v[104:107], v75 offset:38976
	ds_read_b128 v[96:99], v71 offset:32768
	s_waitcnt lgkmcnt(3)
	v_mfma_f32_32x32x16_bf16 v[20:35], v[88:91], v[84:87], v[20:35]
	s_add_u32 m0, s16, 0x400
	s_add_u32 s14, s98, 0x4000
	s_addc_u32 s15, s99, 0
	global_load_lds_dwordx4 v69, s[14:15]
	ds_read_b128 v[100:103], v71 offset:36864
	s_waitcnt lgkmcnt(3)
	v_mfma_f32_32x32x16_bf16 v[36:51], v[92:95], v[80:83], v[36:51]
	s_add_u32 m0, s16, 0x800
	s_add_u32 s14, s98, 0x8000
	s_addc_u32 s15, s99, 0
	global_load_lds_dwordx4 v68, s[14:15]
	ds_read_b128 v[108:111], v75 offset:43072
	v_mfma_f32_32x32x16_bf16 v[4:19], v[92:95], v[84:87], v[4:19]
	s_add_u32 m0, s16, 0xc00
	s_add_u32 s14, s98, 0xc000
	s_addc_u32 s15, s99, 0
	global_load_lds_dwordx4 v69, s[14:15]
	s_waitcnt lgkmcnt(2)
	v_mfma_f32_32x32x16_bf16 v[52:67], v[104:107], v[96:99], v[52:67]
	s_add_u32 m0, s16, 0x4000
	s_nop 0
	global_load_lds_dwordx4 v68, s[100:101]
	ds_read_b128 v[120:123], v76 offset:38976
	ds_read_b128 v[112:115], v72 offset:32768
	s_waitcnt lgkmcnt(3)
	v_mfma_f32_32x32x16_bf16 v[20:35], v[104:107], v[100:103], v[20:35]
	s_add_u32 m0, s16, 0x4400
	s_add_u32 s14, s100, 0x4000
	s_addc_u32 s15, s101, 0
	global_load_lds_dwordx4 v69, s[14:15]
	ds_read_b128 v[116:119], v72 offset:36864
	s_waitcnt lgkmcnt(3)
	v_mfma_f32_32x32x16_bf16 v[36:51], v[108:111], v[96:99], v[36:51]
	s_add_u32 m0, s16, 0x4800
	s_add_u32 s14, s100, 0x8000
	s_addc_u32 s15, s101, 0
	global_load_lds_dwordx4 v68, s[14:15]
	ds_read_b128 v[124:127], v76 offset:43072
	v_mfma_f32_32x32x16_bf16 v[4:19], v[108:111], v[100:103], v[4:19]
	s_add_u32 m0, s16, 0x4c00
	s_add_u32 s14, s100, 0xc000
	s_addc_u32 s15, s101, 0
	global_load_lds_dwordx4 v69, s[14:15]
	s_waitcnt lgkmcnt(2)
	v_mfma_f32_32x32x16_bf16 v[52:67], v[120:123], v[112:115], v[52:67]
	s_add_u32 s98, s98, 0x80
	s_addc_u32 s99, s99, 0
	s_add_u32 s100, s100, 0x80
	s_addc_u32 s101, s101, 0
	ds_read_b128 v[88:91], v77 offset:38976
	ds_read_b128 v[80:83], v73 offset:32768
	s_waitcnt lgkmcnt(3)
	v_mfma_f32_32x32x16_bf16 v[20:35], v[120:123], v[116:119], v[20:35]
	global_load_dwordx4 v[182:185], v242, s[30:31] offset:16
	s_add_u32 s30, s30, 0x10000
	s_addc_u32 s31, s31, 0
	ds_read_b128 v[84:87], v73 offset:36864
	s_waitcnt lgkmcnt(3)
	v_mfma_f32_32x32x16_bf16 v[36:51], v[124:127], v[112:115], v[36:51]
	ds_read_b128 v[92:95], v77 offset:43072
	v_mfma_f32_32x32x16_bf16 v[4:19], v[124:127], v[116:119], v[4:19]
	s_waitcnt lgkmcnt(2)
	v_mfma_f32_32x32x16_bf16 v[52:67], v[88:91], v[80:83], v[52:67]
	s_waitcnt lgkmcnt(1)
	v_mfma_f32_32x32x16_bf16 v[20:35], v[88:91], v[84:87], v[20:35]
	s_waitcnt lgkmcnt(0)
	v_mfma_f32_32x32x16_bf16 v[36:51], v[92:95], v[80:83], v[36:51]
	v_mfma_f32_32x32x16_bf16 v[4:19], v[92:95], v[84:87], v[4:19]
	s_waitcnt vmcnt(1)
	s_barrier
	ds_read_b128 v[88:91], v74 offset:0
	ds_read_b128 v[80:83], v70 offset:0
	ds_read_b128 v[84:87], v70 offset:4096
	ds_read_b128 v[92:95], v74 offset:4096
	s_waitcnt lgkmcnt(2)
	v_mfma_f32_32x32x16_bf16 v[52:67], v[88:91], v[80:83], v[52:67]
	s_add_u32 m0, s16, 0x8000
	s_nop 0
	global_load_lds_dwordx4 v68, s[98:99]
	ds_read_b128 v[104:107], v75 offset:0
	ds_read_b128 v[96:99], v71 offset:0
	s_waitcnt lgkmcnt(3)
	v_mfma_f32_32x32x16_bf16 v[20:35], v[88:91], v[84:87], v[20:35]
	s_add_u32 m0, s16, 0x8400
	s_add_u32 s14, s98, 0x4000
	s_addc_u32 s15, s99, 0
	global_load_lds_dwordx4 v69, s[14:15]
	ds_read_b128 v[100:103], v71 offset:4096
	s_waitcnt lgkmcnt(3)
	v_mfma_f32_32x32x16_bf16 v[36:51], v[92:95], v[80:83], v[36:51]
	s_add_u32 m0, s16, 0x8800
	s_add_u32 s14, s98, 0x8000
	s_addc_u32 s15, s99, 0
	global_load_lds_dwordx4 v68, s[14:15]
	ds_read_b128 v[108:111], v75 offset:4096
	v_mfma_f32_32x32x16_bf16 v[4:19], v[92:95], v[84:87], v[4:19]
	s_add_u32 m0, s16, 0x8c00
	s_add_u32 s14, s98, 0xc000
	s_addc_u32 s15, s99, 0
	global_load_lds_dwordx4 v69, s[14:15]
	s_waitcnt lgkmcnt(2)
	v_mfma_f32_32x32x16_bf16 v[52:67], v[104:107], v[96:99], v[52:67]
	s_add_u32 m0, s16, 0xd840
	s_nop 0
	global_load_lds_dwordx4 v68, s[100:101]
	ds_read_b128 v[120:123], v76 offset:0
	ds_read_b128 v[112:115], v72 offset:0
	s_waitcnt lgkmcnt(3)
	v_mfma_f32_32x32x16_bf16 v[20:35], v[104:107], v[100:103], v[20:35]
	s_add_u32 m0, s16, 0xdc40
	s_add_u32 s14, s100, 0x4000
	s_addc_u32 s15, s101, 0
	global_load_lds_dwordx4 v69, s[14:15]
	ds_read_b128 v[116:119], v72 offset:4096
	s_waitcnt lgkmcnt(3)
	v_mfma_f32_32x32x16_bf16 v[36:51], v[108:111], v[96:99], v[36:51]
	s_add_u32 m0, s16, 0xe040
	s_add_u32 s14, s100, 0x8000
	s_addc_u32 s15, s101, 0
	global_load_lds_dwordx4 v68, s[14:15]
	ds_read_b128 v[124:127], v76 offset:4096
	v_mfma_f32_32x32x16_bf16 v[4:19], v[108:111], v[100:103], v[4:19]
	s_add_u32 m0, s16, 0xe440
	s_add_u32 s14, s100, 0xc000
	s_addc_u32 s15, s101, 0
	global_load_lds_dwordx4 v69, s[14:15]
	s_waitcnt lgkmcnt(2)
	v_mfma_f32_32x32x16_bf16 v[52:67], v[120:123], v[112:115], v[52:67]
	s_add_u32 s98, s98, 0x80
	s_addc_u32 s99, s99, 0
	s_add_u32 s100, s100, 0x80
	s_addc_u32 s101, s101, 0
	ds_read_b128 v[88:91], v77 offset:0
	ds_read_b128 v[80:83], v73 offset:0
	s_waitcnt lgkmcnt(3)
	v_mfma_f32_32x32x16_bf16 v[20:35], v[120:123], v[116:119], v[20:35]
	global_load_dwordx4 v[186:189], v242, s[30:31]
	ds_read_b128 v[84:87], v73 offset:4096
	s_waitcnt lgkmcnt(3)
	v_mfma_f32_32x32x16_bf16 v[36:51], v[124:127], v[112:115], v[36:51]
	ds_read_b128 v[92:95], v77 offset:4096
	v_mfma_f32_32x32x16_bf16 v[4:19], v[124:127], v[116:119], v[4:19]
	s_waitcnt lgkmcnt(2)
	v_mfma_f32_32x32x16_bf16 v[52:67], v[88:91], v[80:83], v[52:67]
	s_waitcnt lgkmcnt(1)
	v_mfma_f32_32x32x16_bf16 v[20:35], v[88:91], v[84:87], v[20:35]
	s_waitcnt lgkmcnt(0)
	v_mfma_f32_32x32x16_bf16 v[36:51], v[92:95], v[80:83], v[36:51]
	v_mfma_f32_32x32x16_bf16 v[4:19], v[92:95], v[84:87], v[4:19]
	s_waitcnt vmcnt(1)
	s_barrier
; template <int NI, bool DEEP = true>
; DEV void gemm_tile(f32x16 (&acc)[2][NI], const bf16* __restrict__ A, int lda, const bf16* __restrict__ Bt, int ldb,
;                    int K, bf16* sA, bf16* sB) {
;     ...
;   G_LOAD(ra0, rb0, 0)
;   if (DEEP) {
;     if (64 < K) G_LOAD(ra1, rb1, 64)
;     for (int k0 = 0; k0 < K; k0 += 128) {
;       G_STEP(ra0, rb0, k0 + 128)
;       if (k0 + 64 < K) G_STEP(ra1, rb1, k0 + 192)
;     }
	ds_read_b128 v[88:91], v74 offset:38976
	ds_read_b128 v[80:83], v70 offset:32768
	ds_read_b128 v[84:87], v70 offset:36864
	ds_read_b128 v[92:95], v74 offset:43072
	s_waitcnt lgkmcnt(2)
	v_mfma_f32_32x32x16_bf16 v[52:67], v[88:91], v[80:83], v[52:67]
	s_add_u32 m0, s16, 0x0
	s_nop 0
	global_load_lds_dwordx4 v68, s[98:99]
	ds_read_b128 v[104:107], v75 offset:38976
	ds_read_b128 v[96:99], v71 offset:32768
	s_waitcnt lgkmcnt(3)
	v_mfma_f32_32x32x16_bf16 v[20:35], v[88:91], v[84:87], v[20:35]
	s_add_u32 m0, s16, 0x400
	s_add_u32 s14, s98, 0x4000
	s_addc_u32 s15, s99, 0
	global_load_lds_dwordx4 v69, s[14:15]
	ds_read_b128 v[100:103], v71 offset:36864
	s_waitcnt lgkmcnt(3)
	v_mfma_f32_32x32x16_bf16 v[36:51], v[92:95], v[80:83], v[36:51]
	s_add_u32 m0, s16, 0x800
	s_add_u32 s14, s98, 0x8000
	s_addc_u32 s15, s99, 0
	global_load_lds_dwordx4 v68, s[14:15]
	ds_read_b128 v[108:111], v75 offset:43072
	v_mfma_f32_32x32x16_bf16 v[4:19], v[92:95], v[84:87], v[4:19]
	s_add_u32 m0, s16, 0xc00
	s_add_u32 s14, s98, 0xc000
	s_addc_u32 s15, s99, 0
	global_load_lds_dwordx4 v69, s[14:15]
	s_waitcnt lgkmcnt(2)
	v_mfma_f32_32x32x16_bf16 v[52:67], v[104:107], v[96:99], v[52:67]
	s_add_u32 m0, s16, 0x4000
	s_nop 0
	global_load_lds_dwordx4 v68, s[100:101]
	ds_read_b128 v[120:123], v76 offset:38976
	ds_read_b128 v[112:115], v72 offset:32768
	s_waitcnt lgkmcnt(3)
	v_mfma_f32_32x32x16_bf16 v[20:35], v[104:107], v[100:103], v[20:35]
	s_add_u32 m0, s16, 0x4400
	s_add_u32 s14, s100, 0x4000
	s_addc_u32 s15, s101, 0
	global_load_lds_dwordx4 v69, s[14:15]
	ds_read_b128 v[116:119], v72 offset:36864
	s_waitcnt lgkmcnt(3)
	v_mfma_f32_32x32x16_bf16 v[36:51], v[108:111], v[96:99], v[36:51]
	s_add_u32 m0, s16, 0x4800
	s_add_u32 s14, s100, 0x8000
	s_addc_u32 s15, s101, 0
	global_load_lds_dwordx4 v68, s[14:15]
	ds_read_b128 v[124:127], v76 offset:43072
	v_mfma_f32_32x32x16_bf16 v[4:19], v[108:111], v[100:103], v[4:19]
	s_add_u32 m0, s16, 0x4c00
	s_add_u32 s14, s100, 0xc000
	s_addc_u32 s15, s101, 0
	global_load_lds_dwordx4 v69, s[14:15]
	s_waitcnt lgkmcnt(2)
	v_mfma_f32_32x32x16_bf16 v[52:67], v[120:123], v[112:115], v[52:67]
	s_add_u32 s98, s98, 0x80
	s_addc_u32 s99, s99, 0
	s_add_u32 s100, s100, 0x80
	s_addc_u32 s101, s101, 0
	ds_read_b128 v[88:91], v77 offset:38976
	ds_read_b128 v[80:83], v73 offset:32768
	s_waitcnt lgkmcnt(3)
	v_mfma_f32_32x32x16_bf16 v[20:35], v[120:123], v[116:119], v[20:35]
	global_load_dwordx4 v[190:193], v242, s[30:31] offset:16
	s_add_u32 s30, s30, 0x10000
	s_addc_u32 s31, s31, 0
	ds_read_b128 v[84:87], v73 offset:36864
	s_waitcnt lgkmcnt(3)
	v_mfma_f32_32x32x16_bf16 v[36:51], v[124:127], v[112:115], v[36:51]
	ds_read_b128 v[92:95], v77 offset:43072
	v_mfma_f32_32x32x16_bf16 v[4:19], v[124:127], v[116:119], v[4:19]
	s_waitcnt lgkmcnt(2)
	v_mfma_f32_32x32x16_bf16 v[52:67], v[88:91], v[80:83], v[52:67]
	s_waitcnt lgkmcnt(1)
	v_mfma_f32_32x32x16_bf16 v[20:35], v[88:91], v[84:87], v[20:35]
	s_waitcnt lgkmcnt(0)
	v_mfma_f32_32x32x16_bf16 v[36:51], v[92:95], v[80:83], v[36:51]
	v_mfma_f32_32x32x16_bf16 v[4:19], v[92:95], v[84:87], v[4:19]
	s_waitcnt vmcnt(1)
	s_barrier
	ds_read_b128 v[88:91], v74 offset:0
	ds_read_b128 v[80:83], v70 offset:0
	ds_read_b128 v[84:87], v70 offset:4096
	ds_read_b128 v[92:95], v74 offset:4096
	s_waitcnt lgkmcnt(2)
	v_mfma_f32_32x32x16_bf16 v[52:67], v[88:91], v[80:83], v[52:67]
	s_add_u32 m0, s16, 0x8000
	s_nop 0
	global_load_lds_dwordx4 v68, s[98:99]
	ds_read_b128 v[104:107], v75 offset:0
	ds_read_b128 v[96:99], v71 offset:0
	s_waitcnt lgkmcnt(3)
	v_mfma_f32_32x32x16_bf16 v[20:35], v[88:91], v[84:87], v[20:35]
	s_add_u32 m0, s16, 0x8400
	s_add_u32 s14, s98, 0x4000
	s_addc_u32 s15, s99, 0
	global_load_lds_dwordx4 v69, s[14:15]
	ds_read_b128 v[100:103], v71 offset:4096
	s_waitcnt lgkmcnt(3)
	v_mfma_f32_32x32x16_bf16 v[36:51], v[92:95], v[80:83], v[36:51]
	s_add_u32 m0, s16, 0x8800
	s_add_u32 s14, s98, 0x8000
	s_addc_u32 s15, s99, 0
	global_load_lds_dwordx4 v68, s[14:15]
	ds_read_b128 v[108:111], v75 offset:4096
	v_mfma_f32_32x32x16_bf16 v[4:19], v[92:95], v[84:87], v[4:19]
	s_add_u32 m0, s16, 0x8c00
	s_add_u32 s14, s98, 0xc000
	s_addc_u32 s15, s99, 0
	global_load_lds_dwordx4 v69, s[14:15]
	s_waitcnt lgkmcnt(2)
	v_mfma_f32_32x32x16_bf16 v[52:67], v[104:107], v[96:99], v[52:67]
	s_add_u32 m0, s16, 0xd840
	s_nop 0
	global_load_lds_dwordx4 v68, s[100:101]
	ds_read_b128 v[120:123], v76 offset:0
	ds_read_b128 v[112:115], v72 offset:0
	s_waitcnt lgkmcnt(3)
	v_mfma_f32_32x32x16_bf16 v[20:35], v[104:107], v[100:103], v[20:35]
	s_add_u32 m0, s16, 0xdc40
	s_add_u32 s14, s100, 0x4000
	s_addc_u32 s15, s101, 0
	global_load_lds_dwordx4 v69, s[14:15]
	ds_read_b128 v[116:119], v72 offset:4096
	s_waitcnt lgkmcnt(3)
	v_mfma_f32_32x32x16_bf16 v[36:51], v[108:111], v[96:99], v[36:51]
	s_add_u32 m0, s16, 0xe040
	s_add_u32 s14, s100, 0x8000
	s_addc_u32 s15, s101, 0
	global_load_lds_dwordx4 v68, s[14:15]
	ds_read_b128 v[124:127], v76 offset:4096
	v_mfma_f32_32x32x16_bf16 v[4:19], v[108:111], v[100:103], v[4:19]
	s_add_u32 m0, s16, 0xe440
	s_add_u32 s14, s100, 0xc000
	s_addc_u32 s15, s101, 0
	global_load_lds_dwordx4 v69, s[14:15]
	s_waitcnt lgkmcnt(2)
	v_mfma_f32_32x32x16_bf16 v[52:67], v[120:123], v[112:115], v[52:67]
	s_add_u32 s98, s98, 0x80
	s_addc_u32 s99, s99, 0
	s_add_u32 s100, s100, 0x80
	s_addc_u32 s101, s101, 0
	ds_read_b128 v[88:91], v77 offset:0
	ds_read_b128 v[80:83], v73 offset:0
	s_waitcnt lgkmcnt(3)
	v_mfma_f32_32x32x16_bf16 v[20:35], v[120:123], v[116:119], v[20:35]
	global_load_dwordx4 v[210:213], v242, s[30:31]
	ds_read_b128 v[84:87], v73 offset:4096
	s_waitcnt lgkmcnt(3)
	v_mfma_f32_32x32x16_bf16 v[36:51], v[124:127], v[112:115], v[36:51]
	ds_read_b128 v[92:95], v77 offset:4096
	v_mfma_f32_32x32x16_bf16 v[4:19], v[124:127], v[116:119], v[4:19]
	s_waitcnt lgkmcnt(2)
	v_mfma_f32_32x32x16_bf16 v[52:67], v[88:91], v[80:83], v[52:67]
	s_waitcnt lgkmcnt(1)
	v_mfma_f32_32x32x16_bf16 v[20:35], v[88:91], v[84:87], v[20:35]
	s_waitcnt lgkmcnt(0)
	v_mfma_f32_32x32x16_bf16 v[36:51], v[92:95], v[80:83], v[36:51]
	v_mfma_f32_32x32x16_bf16 v[4:19], v[92:95], v[84:87], v[4:19]
	s_waitcnt vmcnt(1)
	s_barrier
; template <int NI, bool DEEP = true>
; DEV void gemm_tile(f32x16 (&acc)[2][NI], const bf16* __restrict__ A, int lda, const bf16* __restrict__ Bt, int ldb,
;                    int K, bf16* sA, bf16* sB) {
;     ...
;   G_LOAD(ra0, rb0, 0)
;   if (DEEP) {
;     if (64 < K) G_LOAD(ra1, rb1, 64)
;     for (int k0 = 0; k0 < K; k0 += 128) {
;       G_STEP(ra0, rb0, k0 + 128)
;       if (k0 + 64 < K) G_STEP(ra1, rb1, k0 + 192)
;     }
	ds_read_b128 v[88:91], v74 offset:38976
	ds_read_b128 v[80:83], v70 offset:32768
	ds_read_b128 v[84:87], v70 offset:36864
	ds_read_b128 v[92:95], v74 offset:43072
	s_waitcnt lgkmcnt(2)
	v_mfma_f32_32x32x16_bf16 v[52:67], v[88:91], v[80:83], v[52:67]
	s_add_u32 m0, s16, 0x0
	s_nop 0
	global_load_lds_dwordx4 v68, s[98:99]
	ds_read_b128 v[104:107], v75 offset:38976
	ds_read_b128 v[96:99], v71 offset:32768
	s_waitcnt lgkmcnt(3)
	v_mfma_f32_32x32x16_bf16 v[20:35], v[88:91], v[84:87], v[20:35]
	s_add_u32 m0, s16, 0x400
	s_add_u32 s14, s98, 0x4000
	s_addc_u32 s15, s99, 0
	global_load_lds_dwordx4 v69, s[14:15]
	ds_read_b128 v[100:103], v71 offset:36864
	s_waitcnt lgkmcnt(3)
	v_mfma_f32_32x32x16_bf16 v[36:51], v[92:95], v[80:83], v[36:51]
	s_add_u32 m0, s16, 0x800
	s_add_u32 s14, s98, 0x8000
	s_addc_u32 s15, s99, 0
	global_load_lds_dwordx4 v68, s[14:15]
	ds_read_b128 v[108:111], v75 offset:43072
	v_mfma_f32_32x32x16_bf16 v[4:19], v[92:95], v[84:87], v[4:19]
	s_add_u32 m0, s16, 0xc00
	s_add_u32 s14, s98, 0xc000
	s_addc_u32 s15, s99, 0
	global_load_lds_dwordx4 v69, s[14:15]
	s_waitcnt lgkmcnt(2)
	v_mfma_f32_32x32x16_bf16 v[52:67], v[104:107], v[96:99], v[52:67]
	s_add_u32 m0, s16, 0x4000
	s_nop 0
	global_load_lds_dwordx4 v68, s[100:101]
	ds_read_b128 v[120:123], v76 offset:38976
	ds_read_b128 v[112:115], v72 offset:32768
	s_waitcnt lgkmcnt(3)
	v_mfma_f32_32x32x16_bf16 v[20:35], v[104:107], v[100:103], v[20:35]
	s_add_u32 m0, s16, 0x4400
	s_add_u32 s14, s100, 0x4000
	s_addc_u32 s15, s101, 0
	global_load_lds_dwordx4 v69, s[14:15]
	ds_read_b128 v[116:119], v72 offset:36864
	s_waitcnt lgkmcnt(3)
	v_mfma_f32_32x32x16_bf16 v[36:51], v[108:111], v[96:99], v[36:51]
	s_add_u32 m0, s16, 0x4800
	s_add_u32 s14, s100, 0x8000
	s_addc_u32 s15, s101, 0
	global_load_lds_dwordx4 v68, s[14:15]
	ds_read_b128 v[124:127], v76 offset:43072
	v_mfma_f32_32x32x16_bf16 v[4:19], v[108:111], v[100:103], v[4:19]
	s_add_u32 m0, s16, 0x4c00
	s_add_u32 s14, s100, 0xc000
	s_addc_u32 s15, s101, 0
	global_load_lds_dwordx4 v69, s[14:15]
	s_waitcnt lgkmcnt(2)
	v_mfma_f32_32x32x16_bf16 v[52:67], v[120:123], v[112:115], v[52:67]
	s_add_u32 s98, s98, 0x80
	s_addc_u32 s99, s99, 0
	s_add_u32 s100, s100, 0x80
	s_addc_u32 s101, s101, 0
	ds_read_b128 v[88:91], v77 offset:38976
	ds_read_b128 v[80:83], v73 offset:32768
	s_waitcnt lgkmcnt(3)
	v_mfma_f32_32x32x16_bf16 v[20:35], v[120:123], v[116:119], v[20:35]
	global_load_dwordx4 v[214:217], v242, s[30:31] offset:16
	s_add_u32 s30, s30, 0x10000
	s_addc_u32 s31, s31, 0
	ds_read_b128 v[84:87], v73 offset:36864
	s_waitcnt lgkmcnt(3)
	v_mfma_f32_32x32x16_bf16 v[36:51], v[124:127], v[112:115], v[36:51]
	ds_read_b128 v[92:95], v77 offset:43072
	v_mfma_f32_32x32x16_bf16 v[4:19], v[124:127], v[116:119], v[4:19]
	s_waitcnt lgkmcnt(2)
	v_mfma_f32_32x32x16_bf16 v[52:67], v[88:91], v[80:83], v[52:67]
	s_waitcnt lgkmcnt(1)
	v_mfma_f32_32x32x16_bf16 v[20:35], v[88:91], v[84:87], v[20:35]
	s_waitcnt lgkmcnt(0)
	v_mfma_f32_32x32x16_bf16 v[36:51], v[92:95], v[80:83], v[36:51]
	v_mfma_f32_32x32x16_bf16 v[4:19], v[92:95], v[84:87], v[4:19]
	s_waitcnt vmcnt(1)
	s_barrier
	ds_read_b128 v[88:91], v74 offset:0
	ds_read_b128 v[80:83], v70 offset:0
	ds_read_b128 v[84:87], v70 offset:4096
	ds_read_b128 v[92:95], v74 offset:4096
	s_waitcnt lgkmcnt(2)
	v_mfma_f32_32x32x16_bf16 v[52:67], v[88:91], v[80:83], v[52:67]
	s_add_u32 m0, s16, 0x8000
	s_nop 0
	global_load_lds_dwordx4 v68, s[98:99]
	ds_read_b128 v[104:107], v75 offset:0
	ds_read_b128 v[96:99], v71 offset:0
	s_waitcnt lgkmcnt(3)
	v_mfma_f32_32x32x16_bf16 v[20:35], v[88:91], v[84:87], v[20:35]
	s_add_u32 m0, s16, 0x8400
	s_add_u32 s14, s98, 0x4000
	s_addc_u32 s15, s99, 0
	global_load_lds_dwordx4 v69, s[14:15]
	ds_read_b128 v[100:103], v71 offset:4096
	s_waitcnt lgkmcnt(3)
	v_mfma_f32_32x32x16_bf16 v[36:51], v[92:95], v[80:83], v[36:51]
	s_add_u32 m0, s16, 0x8800
	s_add_u32 s14, s98, 0x8000
	s_addc_u32 s15, s99, 0
	global_load_lds_dwordx4 v68, s[14:15]
	ds_read_b128 v[108:111], v75 offset:4096
	v_mfma_f32_32x32x16_bf16 v[4:19], v[92:95], v[84:87], v[4:19]
	s_add_u32 m0, s16, 0x8c00
	s_add_u32 s14, s98, 0xc000
	s_addc_u32 s15, s99, 0
	global_load_lds_dwordx4 v69, s[14:15]
	s_waitcnt lgkmcnt(2)
	v_mfma_f32_32x32x16_bf16 v[52:67], v[104:107], v[96:99], v[52:67]
	s_add_u32 m0, s16, 0xd840
	s_nop 0
	global_load_lds_dwordx4 v68, s[100:101]
	ds_read_b128 v[120:123], v76 offset:0
	ds_read_b128 v[112:115], v72 offset:0
	s_waitcnt lgkmcnt(3)
	v_mfma_f32_32x32x16_bf16 v[20:35], v[104:107], v[100:103], v[20:35]
	s_add_u32 m0, s16, 0xdc40
	s_add_u32 s14, s100, 0x4000
	s_addc_u32 s15, s101, 0
	global_load_lds_dwordx4 v69, s[14:15]
	ds_read_b128 v[116:119], v72 offset:4096
	s_waitcnt lgkmcnt(3)
	v_mfma_f32_32x32x16_bf16 v[36:51], v[108:111], v[96:99], v[36:51]
	s_add_u32 m0, s16, 0xe040
	s_add_u32 s14, s100, 0x8000
	s_addc_u32 s15, s101, 0
	global_load_lds_dwordx4 v68, s[14:15]
	ds_read_b128 v[124:127], v76 offset:4096
	v_mfma_f32_32x32x16_bf16 v[4:19], v[108:111], v[100:103], v[4:19]
	s_add_u32 m0, s16, 0xe440
	s_add_u32 s14, s100, 0xc000
	s_addc_u32 s15, s101, 0
	global_load_lds_dwordx4 v69, s[14:15]
	s_waitcnt lgkmcnt(2)
	v_mfma_f32_32x32x16_bf16 v[52:67], v[120:123], v[112:115], v[52:67]
	s_add_u32 s98, s98, 0x80
	s_addc_u32 s99, s99, 0
	s_add_u32 s100, s100, 0x80
	s_addc_u32 s101, s101, 0
	ds_read_b128 v[88:91], v77 offset:0
	ds_read_b128 v[80:83], v73 offset:0
	s_waitcnt lgkmcnt(3)
	v_mfma_f32_32x32x16_bf16 v[20:35], v[120:123], v[116:119], v[20:35]
	global_load_dwordx4 v[218:221], v242, s[30:31]
	ds_read_b128 v[84:87], v73 offset:4096
	s_waitcnt lgkmcnt(3)
	v_mfma_f32_32x32x16_bf16 v[36:51], v[124:127], v[112:115], v[36:51]
	ds_read_b128 v[92:95], v77 offset:4096
	v_mfma_f32_32x32x16_bf16 v[4:19], v[124:127], v[116:119], v[4:19]
	s_waitcnt lgkmcnt(2)
	v_mfma_f32_32x32x16_bf16 v[52:67], v[88:91], v[80:83], v[52:67]
	s_waitcnt lgkmcnt(1)
	v_mfma_f32_32x32x16_bf16 v[20:35], v[88:91], v[84:87], v[20:35]
	s_waitcnt lgkmcnt(0)
	v_mfma_f32_32x32x16_bf16 v[36:51], v[92:95], v[80:83], v[36:51]
	v_mfma_f32_32x32x16_bf16 v[4:19], v[92:95], v[84:87], v[4:19]
	s_waitcnt vmcnt(1)
	s_barrier
; template <int NI, bool DEEP = true>
; DEV void gemm_tile(f32x16 (&acc)[2][NI], const bf16* __restrict__ A, int lda, const bf16* __restrict__ Bt, int ldb,
;                    int K, bf16* sA, bf16* sB) {
;     ...
;   G_LOAD(ra0, rb0, 0)
;   if (DEEP) {
;     if (64 < K) G_LOAD(ra1, rb1, 64)
;     for (int k0 = 0; k0 < K; k0 += 128) {
;       G_STEP(ra0, rb0, k0 + 128)
;       if (k0 + 64 < K) G_STEP(ra1, rb1, k0 + 192)
;     }
	ds_read_b128 v[88:91], v74 offset:38976
	ds_read_b128 v[80:83], v70 offset:32768
	ds_read_b128 v[84:87], v70 offset:36864
	ds_read_b128 v[92:95], v74 offset:43072
	s_waitcnt lgkmcnt(2)
	v_mfma_f32_32x32x16_bf16 v[52:67], v[88:91], v[80:83], v[52:67]
	s_add_u32 m0, s16, 0x0
	s_nop 0
	global_load_lds_dwordx4 v68, s[98:99]
	ds_read_b128 v[104:107], v75 offset:38976
	ds_read_b128 v[96:99], v71 offset:32768
	s_waitcnt lgkmcnt(3)
	v_mfma_f32_32x32x16_bf16 v[20:35], v[88:91], v[84:87], v[20:35]
	s_add_u32 m0, s16, 0x400
	s_add_u32 s14, s98, 0x4000
	s_addc_u32 s15, s99, 0
	global_load_lds_dwordx4 v69, s[14:15]
	ds_read_b128 v[100:103], v71 offset:36864
	s_waitcnt lgkmcnt(3)
	v_mfma_f32_32x32x16_bf16 v[36:51], v[92:95], v[80:83], v[36:51]
	s_add_u32 m0, s16, 0x800
	s_add_u32 s14, s98, 0x8000
	s_addc_u32 s15, s99, 0
	global_load_lds_dwordx4 v68, s[14:15]
	ds_read_b128 v[108:111], v75 offset:43072
	v_mfma_f32_32x32x16_bf16 v[4:19], v[92:95], v[84:87], v[4:19]
	s_add_u32 m0, s16, 0xc00
	s_add_u32 s14, s98, 0xc000
	s_addc_u32 s15, s99, 0
	global_load_lds_dwordx4 v69, s[14:15]
	s_waitcnt lgkmcnt(2)
	v_mfma_f32_32x32x16_bf16 v[52:67], v[104:107], v[96:99], v[52:67]
	s_add_u32 m0, s16, 0x4000
	s_nop 0
	global_load_lds_dwordx4 v68, s[100:101]
	ds_read_b128 v[120:123], v76 offset:38976
	ds_read_b128 v[112:115], v72 offset:32768
	s_waitcnt lgkmcnt(3)
	v_mfma_f32_32x32x16_bf16 v[20:35], v[104:107], v[100:103], v[20:35]
	s_add_u32 m0, s16, 0x4400
	s_add_u32 s14, s100, 0x4000
	s_addc_u32 s15, s101, 0
	global_load_lds_dwordx4 v69, s[14:15]
	ds_read_b128 v[116:119], v72 offset:36864
	s_waitcnt lgkmcnt(3)
	v_mfma_f32_32x32x16_bf16 v[36:51], v[108:111], v[96:99], v[36:51]
	s_add_u32 m0, s16, 0x4800
	s_add_u32 s14, s100, 0x8000
	s_addc_u32 s15, s101, 0
	global_load_lds_dwordx4 v68, s[14:15]
	ds_read_b128 v[124:127], v76 offset:43072
	v_mfma_f32_32x32x16_bf16 v[4:19], v[108:111], v[100:103], v[4:19]
	s_add_u32 m0, s16, 0x4c00
	s_add_u32 s14, s100, 0xc000
	s_addc_u32 s15, s101, 0
	global_load_lds_dwordx4 v69, s[14:15]
	s_waitcnt lgkmcnt(2)
	v_mfma_f32_32x32x16_bf16 v[52:67], v[120:123], v[112:115], v[52:67]
	s_add_u32 s98, s98, 0x80
	s_addc_u32 s99, s99, 0
	s_add_u32 s100, s100, 0x80
	s_addc_u32 s101, s101, 0
	ds_read_b128 v[88:91], v77 offset:38976
	ds_read_b128 v[80:83], v73 offset:32768
	s_waitcnt lgkmcnt(3)
	v_mfma_f32_32x32x16_bf16 v[20:35], v[120:123], v[116:119], v[20:35]
	global_load_dwordx4 v[222:225], v242, s[30:31] offset:16
	s_add_u32 s30, s30, 0x10000
	s_addc_u32 s31, s31, 0
	ds_read_b128 v[84:87], v73 offset:36864
	s_waitcnt lgkmcnt(3)
	v_mfma_f32_32x32x16_bf16 v[36:51], v[124:127], v[112:115], v[36:51]
	ds_read_b128 v[92:95], v77 offset:43072
	v_mfma_f32_32x32x16_bf16 v[4:19], v[124:127], v[116:119], v[4:19]
	s_waitcnt lgkmcnt(2)
	v_mfma_f32_32x32x16_bf16 v[52:67], v[88:91], v[80:83], v[52:67]
	s_waitcnt lgkmcnt(1)
	v_mfma_f32_32x32x16_bf16 v[20:35], v[88:91], v[84:87], v[20:35]
	s_waitcnt lgkmcnt(0)
	v_mfma_f32_32x32x16_bf16 v[36:51], v[92:95], v[80:83], v[36:51]
	v_mfma_f32_32x32x16_bf16 v[4:19], v[92:95], v[84:87], v[4:19]
	s_waitcnt vmcnt(1)
	s_barrier
	ds_read_b128 v[88:91], v74 offset:0
	ds_read_b128 v[80:83], v70 offset:0
	ds_read_b128 v[84:87], v70 offset:4096
	ds_read_b128 v[92:95], v74 offset:4096
	s_waitcnt lgkmcnt(2)
	v_mfma_f32_32x32x16_bf16 v[52:67], v[88:91], v[80:83], v[52:67]
	s_add_u32 m0, s16, 0x8000
	s_nop 0
	global_load_lds_dwordx4 v68, s[98:99]
	ds_read_b128 v[104:107], v75 offset:0
	ds_read_b128 v[96:99], v71 offset:0
	s_waitcnt lgkmcnt(3)
	v_mfma_f32_32x32x16_bf16 v[20:35], v[88:91], v[84:87], v[20:35]
	s_add_u32 m0, s16, 0x8400
	s_add_u32 s14, s98, 0x4000
	s_addc_u32 s15, s99, 0
	global_load_lds_dwordx4 v69, s[14:15]
	ds_read_b128 v[100:103], v71 offset:4096
	s_waitcnt lgkmcnt(3)
	v_mfma_f32_32x32x16_bf16 v[36:51], v[92:95], v[80:83], v[36:51]
	s_add_u32 m0, s16, 0x8800
	s_add_u32 s14, s98, 0x8000
	s_addc_u32 s15, s99, 0
	global_load_lds_dwordx4 v68, s[14:15]
	ds_read_b128 v[108:111], v75 offset:4096
	v_mfma_f32_32x32x16_bf16 v[4:19], v[92:95], v[84:87], v[4:19]
	s_add_u32 m0, s16, 0x8c00
	s_add_u32 s14, s98, 0xc000
	s_addc_u32 s15, s99, 0
	global_load_lds_dwordx4 v69, s[14:15]
	s_waitcnt lgkmcnt(2)
	v_mfma_f32_32x32x16_bf16 v[52:67], v[104:107], v[96:99], v[52:67]
	s_add_u32 m0, s16, 0xd840
	s_nop 0
	global_load_lds_dwordx4 v68, s[100:101]
	ds_read_b128 v[120:123], v76 offset:0
	ds_read_b128 v[112:115], v72 offset:0
	s_waitcnt lgkmcnt(3)
	v_mfma_f32_32x32x16_bf16 v[20:35], v[104:107], v[100:103], v[20:35]
	s_add_u32 m0, s16, 0xdc40
	s_add_u32 s14, s100, 0x4000
	s_addc_u32 s15, s101, 0
	global_load_lds_dwordx4 v69, s[14:15]
	ds_read_b128 v[116:119], v72 offset:4096
	s_waitcnt lgkmcnt(3)
	v_mfma_f32_32x32x16_bf16 v[36:51], v[108:111], v[96:99], v[36:51]
	s_add_u32 m0, s16, 0xe040
	s_add_u32 s14, s100, 0x8000
	s_addc_u32 s15, s101, 0
	global_load_lds_dwordx4 v68, s[14:15]
	ds_read_b128 v[124:127], v76 offset:4096
	v_mfma_f32_32x32x16_bf16 v[4:19], v[108:111], v[100:103], v[4:19]
	s_add_u32 m0, s16, 0xe440
	s_add_u32 s14, s100, 0xc000
	s_addc_u32 s15, s101, 0
	global_load_lds_dwordx4 v69, s[14:15]
	s_waitcnt lgkmcnt(2)
	v_mfma_f32_32x32x16_bf16 v[52:67], v[120:123], v[112:115], v[52:67]
	s_add_u32 s98, s98, 0x80
	s_addc_u32 s99, s99, 0
	s_add_u32 s100, s100, 0x80
	s_addc_u32 s101, s101, 0
	ds_read_b128 v[88:91], v77 offset:0
	ds_read_b128 v[80:83], v73 offset:0
	s_waitcnt lgkmcnt(3)
	v_mfma_f32_32x32x16_bf16 v[20:35], v[120:123], v[116:119], v[20:35]
	global_load_dwordx4 v[226:229], v242, s[30:31]
	ds_read_b128 v[84:87], v73 offset:4096
	s_waitcnt lgkmcnt(3)
	v_mfma_f32_32x32x16_bf16 v[36:51], v[124:127], v[112:115], v[36:51]
	ds_read_b128 v[92:95], v77 offset:4096
	v_mfma_f32_32x32x16_bf16 v[4:19], v[124:127], v[116:119], v[4:19]
	s_waitcnt lgkmcnt(2)
	v_mfma_f32_32x32x16_bf16 v[52:67], v[88:91], v[80:83], v[52:67]
	s_waitcnt lgkmcnt(1)
	v_mfma_f32_32x32x16_bf16 v[20:35], v[88:91], v[84:87], v[20:35]
	s_waitcnt lgkmcnt(0)
	v_mfma_f32_32x32x16_bf16 v[36:51], v[92:95], v[80:83], v[36:51]
	v_mfma_f32_32x32x16_bf16 v[4:19], v[92:95], v[84:87], v[4:19]
	s_waitcnt vmcnt(1)
	s_barrier
; template <int NI, bool DEEP = true>
; DEV void gemm_tile(f32x16 (&acc)[2][NI], const bf16* __restrict__ A, int lda, const bf16* __restrict__ Bt, int ldb,
;                    int K, bf16* sA, bf16* sB) {
;     ...
;   G_LOAD(ra0, rb0, 0)
;   if (DEEP) {
;     if (64 < K) G_LOAD(ra1, rb1, 64)
;     for (int k0 = 0; k0 < K; k0 += 128) {
;       G_STEP(ra0, rb0, k0 + 128)
;       if (k0 + 64 < K) G_STEP(ra1, rb1, k0 + 192)
;     }
	ds_read_b128 v[88:91], v74 offset:38976
	ds_read_b128 v[80:83], v70 offset:32768
	ds_read_b128 v[84:87], v70 offset:36864
	ds_read_b128 v[92:95], v74 offset:43072
	s_waitcnt lgkmcnt(2)
	v_mfma_f32_32x32x16_bf16 v[52:67], v[88:91], v[80:83], v[52:67]
	s_add_u32 m0, s16, 0x0
	s_nop 0
	global_load_lds_dwordx4 v68, s[98:99]
	ds_read_b128 v[104:107], v75 offset:38976
	ds_read_b128 v[96:99], v71 offset:32768
	s_waitcnt lgkmcnt(3)
	v_mfma_f32_32x32x16_bf16 v[20:35], v[88:91], v[84:87], v[20:35]
	s_add_u32 m0, s16, 0x400
	s_add_u32 s14, s98, 0x4000
	s_addc_u32 s15, s99, 0
	global_load_lds_dwordx4 v69, s[14:15]
	ds_read_b128 v[100:103], v71 offset:36864
	s_waitcnt lgkmcnt(3)
	v_mfma_f32_32x32x16_bf16 v[36:51], v[92:95], v[80:83], v[36:51]
	s_add_u32 m0, s16, 0x800
	s_add_u32 s14, s98, 0x8000
	s_addc_u32 s15, s99, 0
	global_load_lds_dwordx4 v68, s[14:15]
	ds_read_b128 v[108:111], v75 offset:43072
	v_mfma_f32_32x32x16_bf16 v[4:19], v[92:95], v[84:87], v[4:19]
	s_add_u32 m0, s16, 0xc00
	s_add_u32 s14, s98, 0xc000
	s_addc_u32 s15, s99, 0
	global_load_lds_dwordx4 v69, s[14:15]
	s_waitcnt lgkmcnt(2)
	v_mfma_f32_32x32x16_bf16 v[52:67], v[104:107], v[96:99], v[52:67]
	s_add_u32 m0, s16, 0x4000
	s_nop 0
	global_load_lds_dwordx4 v68, s[100:101]
	ds_read_b128 v[120:123], v76 offset:38976
	ds_read_b128 v[112:115], v72 offset:32768
	s_waitcnt lgkmcnt(3)
	v_mfma_f32_32x32x16_bf16 v[20:35], v[104:107], v[100:103], v[20:35]
	s_add_u32 m0, s16, 0x4400
	s_add_u32 s14, s100, 0x4000
	s_addc_u32 s15, s101, 0
	global_load_lds_dwordx4 v69, s[14:15]
	ds_read_b128 v[116:119], v72 offset:36864
	s_waitcnt lgkmcnt(3)
	v_mfma_f32_32x32x16_bf16 v[36:51], v[108:111], v[96:99], v[36:51]
	s_add_u32 m0, s16, 0x4800
	s_add_u32 s14, s100, 0x8000
	s_addc_u32 s15, s101, 0
	global_load_lds_dwordx4 v68, s[14:15]
	ds_read_b128 v[124:127], v76 offset:43072
	v_mfma_f32_32x32x16_bf16 v[4:19], v[108:111], v[100:103], v[4:19]
	s_add_u32 m0, s16, 0x4c00
	s_add_u32 s14, s100, 0xc000
	s_addc_u32 s15, s101, 0
	global_load_lds_dwordx4 v69, s[14:15]
	s_waitcnt lgkmcnt(2)
	v_mfma_f32_32x32x16_bf16 v[52:67], v[120:123], v[112:115], v[52:67]
	s_add_u32 s98, s98, 0x80
	s_addc_u32 s99, s99, 0
	s_add_u32 s100, s100, 0x80
	s_addc_u32 s101, s101, 0
	ds_read_b128 v[88:91], v77 offset:38976
	ds_read_b128 v[80:83], v73 offset:32768
	s_waitcnt lgkmcnt(3)
	v_mfma_f32_32x32x16_bf16 v[20:35], v[120:123], v[116:119], v[20:35]
	global_load_dwordx4 v[230:233], v242, s[30:31] offset:16
	s_add_u32 s30, s30, 0x10000
	s_addc_u32 s31, s31, 0
	ds_read_b128 v[84:87], v73 offset:36864
	s_waitcnt lgkmcnt(3)
	v_mfma_f32_32x32x16_bf16 v[36:51], v[124:127], v[112:115], v[36:51]
	ds_read_b128 v[92:95], v77 offset:43072
	v_mfma_f32_32x32x16_bf16 v[4:19], v[124:127], v[116:119], v[4:19]
	s_waitcnt lgkmcnt(2)
	v_mfma_f32_32x32x16_bf16 v[52:67], v[88:91], v[80:83], v[52:67]
	s_waitcnt lgkmcnt(1)
	v_mfma_f32_32x32x16_bf16 v[20:35], v[88:91], v[84:87], v[20:35]
	s_waitcnt lgkmcnt(0)
	v_mfma_f32_32x32x16_bf16 v[36:51], v[92:95], v[80:83], v[36:51]
	v_mfma_f32_32x32x16_bf16 v[4:19], v[92:95], v[84:87], v[4:19]
	s_waitcnt vmcnt(1)
	s_barrier
; template <int NI, bool DEEP = true>
; DEV void gemm_tile(f32x16 (&acc)[2][NI], const bf16* __restrict__ A, int lda, const bf16* __restrict__ Bt, int ldb,
;                    int K, bf16* sA, bf16* sB) {
;     ...
;   G_LOAD(ra0, rb0, 0)
;   if (DEEP) {
;     if (64 < K) G_LOAD(ra1, rb1, 64)
;     for (int k0 = 0; k0 < K; k0 += 128) {
;       G_STEP(ra0, rb0, k0 + 128)
;       if (k0 + 64 < K) G_STEP(ra1, rb1, k0 + 192)
;     }
;   } else {
;     for (int k0 = 0; k0 < K; k0 += 64) G_STEP(ra0, rb0, k0 + 64)
;   }
	ds_read_b128 v[88:91], v74 offset:0
	ds_read_b128 v[80:83], v70 offset:0
	ds_read_b128 v[84:87], v70 offset:4096
	ds_read_b128 v[92:95], v74 offset:4096
	s_waitcnt lgkmcnt(2)
	v_mfma_f32_32x32x16_bf16 v[52:67], v[88:91], v[80:83], v[52:67]
	s_add_u32 m0, s16, 0x8000
	s_nop 0
	global_load_lds_dwordx4 v68, s[98:99]
	ds_read_b128 v[104:107], v75 offset:0
	ds_read_b128 v[96:99], v71 offset:0
	s_waitcnt lgkmcnt(3)
	v_mfma_f32_32x32x16_bf16 v[20:35], v[88:91], v[84:87], v[20:35]
	s_add_u32 m0, s16, 0x8400
	s_add_u32 s14, s98, 0x4000
	s_addc_u32 s15, s99, 0
	global_load_lds_dwordx4 v69, s[14:15]
	ds_read_b128 v[100:103], v71 offset:4096
	s_waitcnt lgkmcnt(3)
	v_mfma_f32_32x32x16_bf16 v[36:51], v[92:95], v[80:83], v[36:51]
	s_add_u32 m0, s16, 0x8800
	s_add_u32 s14, s98, 0x8000
	s_addc_u32 s15, s99, 0
	global_load_lds_dwordx4 v68, s[14:15]
	ds_read_b128 v[108:111], v75 offset:4096
	v_mfma_f32_32x32x16_bf16 v[4:19], v[92:95], v[84:87], v[4:19]
	s_add_u32 m0, s16, 0x8c00
	s_add_u32 s14, s98, 0xc000
	s_addc_u32 s15, s99, 0
	global_load_lds_dwordx4 v69, s[14:15]
	s_waitcnt lgkmcnt(2)
	v_mfma_f32_32x32x16_bf16 v[52:67], v[104:107], v[96:99], v[52:67]
	s_add_u32 m0, s16, 0xd840
	s_nop 0
	global_load_lds_dwordx4 v68, s[100:101]
	ds_read_b128 v[120:123], v76 offset:0
	ds_read_b128 v[112:115], v72 offset:0
	s_waitcnt lgkmcnt(3)
	v_mfma_f32_32x32x16_bf16 v[20:35], v[104:107], v[100:103], v[20:35]
	s_add_u32 m0, s16, 0xdc40
	s_add_u32 s14, s100, 0x4000
	s_addc_u32 s15, s101, 0
	global_load_lds_dwordx4 v69, s[14:15]
	ds_read_b128 v[116:119], v72 offset:4096
	s_waitcnt lgkmcnt(3)
	v_mfma_f32_32x32x16_bf16 v[36:51], v[108:111], v[96:99], v[36:51]
	s_add_u32 m0, s16, 0xe040
	s_add_u32 s14, s100, 0x8000
	s_addc_u32 s15, s101, 0
	global_load_lds_dwordx4 v68, s[14:15]
	ds_read_b128 v[124:127], v76 offset:4096
	v_mfma_f32_32x32x16_bf16 v[4:19], v[108:111], v[100:103], v[4:19]
	s_add_u32 m0, s16, 0xe440
	s_add_u32 s14, s100, 0xc000
	s_addc_u32 s15, s101, 0
	global_load_lds_dwordx4 v69, s[14:15]
	s_waitcnt lgkmcnt(2)
	v_mfma_f32_32x32x16_bf16 v[52:67], v[120:123], v[112:115], v[52:67]
	s_add_u32 s98, s98, 0x80
	s_addc_u32 s99, s99, 0
	s_add_u32 s100, s100, 0x80
	s_addc_u32 s101, s101, 0
	ds_read_b128 v[88:91], v77 offset:0
	ds_read_b128 v[80:83], v73 offset:0
	s_waitcnt lgkmcnt(3)
	v_mfma_f32_32x32x16_bf16 v[20:35], v[120:123], v[116:119], v[20:35]
	global_load_dwordx4 v[234:237], v242, s[30:31]
	ds_read_b128 v[84:87], v73 offset:4096
	s_waitcnt lgkmcnt(3)
	v_mfma_f32_32x32x16_bf16 v[36:51], v[124:127], v[112:115], v[36:51]
	ds_read_b128 v[92:95], v77 offset:4096
	v_mfma_f32_32x32x16_bf16 v[4:19], v[124:127], v[116:119], v[4:19]
	s_waitcnt lgkmcnt(2)
	v_mfma_f32_32x32x16_bf16 v[52:67], v[88:91], v[80:83], v[52:67]
	s_waitcnt lgkmcnt(1)
	v_mfma_f32_32x32x16_bf16 v[20:35], v[88:91], v[84:87], v[20:35]
	s_waitcnt lgkmcnt(0)
	v_mfma_f32_32x32x16_bf16 v[36:51], v[92:95], v[80:83], v[36:51]
	v_mfma_f32_32x32x16_bf16 v[4:19], v[92:95], v[84:87], v[4:19]
	s_waitcnt vmcnt(1)
	s_barrier
	ds_read_b128 v[88:91], v74 offset:38976
	ds_read_b128 v[80:83], v70 offset:32768
	ds_read_b128 v[84:87], v70 offset:36864
	ds_read_b128 v[92:95], v74 offset:43072
	s_waitcnt lgkmcnt(2)
	v_mfma_f32_32x32x16_bf16 v[52:67], v[88:91], v[80:83], v[52:67]
	global_load_dwordx4 v[238:241], v242, s[30:31] offset:16
	ds_read_b128 v[104:107], v75 offset:38976
	ds_read_b128 v[96:99], v71 offset:32768
	s_waitcnt lgkmcnt(3)
	v_mfma_f32_32x32x16_bf16 v[20:35], v[88:91], v[84:87], v[20:35]
	ds_read_b128 v[100:103], v71 offset:36864
	s_waitcnt lgkmcnt(3)
	v_mfma_f32_32x32x16_bf16 v[36:51], v[92:95], v[80:83], v[36:51]
	ds_read_b128 v[108:111], v75 offset:43072
	v_mfma_f32_32x32x16_bf16 v[4:19], v[92:95], v[84:87], v[4:19]
	s_waitcnt lgkmcnt(2)
	v_mfma_f32_32x32x16_bf16 v[52:67], v[104:107], v[96:99], v[52:67]
	ds_read_b128 v[120:123], v76 offset:38976
	ds_read_b128 v[112:115], v72 offset:32768
	s_waitcnt lgkmcnt(3)
	v_mfma_f32_32x32x16_bf16 v[20:35], v[104:107], v[100:103], v[20:35]
	ds_read_b128 v[116:119], v72 offset:36864
	s_waitcnt lgkmcnt(3)
	v_mfma_f32_32x32x16_bf16 v[36:51], v[108:111], v[96:99], v[36:51]
	ds_read_b128 v[124:127], v76 offset:43072
	v_mfma_f32_32x32x16_bf16 v[4:19], v[108:111], v[100:103], v[4:19]
	s_waitcnt lgkmcnt(2)
	v_mfma_f32_32x32x16_bf16 v[52:67], v[120:123], v[112:115], v[52:67]
	ds_read_b128 v[88:91], v77 offset:38976
	ds_read_b128 v[80:83], v73 offset:32768
	s_waitcnt lgkmcnt(3)
	v_mfma_f32_32x32x16_bf16 v[20:35], v[120:123], v[116:119], v[20:35]
	ds_read_b128 v[84:87], v73 offset:36864
	s_waitcnt lgkmcnt(3)
	v_mfma_f32_32x32x16_bf16 v[36:51], v[124:127], v[112:115], v[36:51]
	ds_read_b128 v[92:95], v77 offset:43072
	v_mfma_f32_32x32x16_bf16 v[4:19], v[124:127], v[116:119], v[4:19]
	s_waitcnt lgkmcnt(2)
	v_mfma_f32_32x32x16_bf16 v[52:67], v[88:91], v[80:83], v[52:67]
	s_waitcnt lgkmcnt(1)
	v_mfma_f32_32x32x16_bf16 v[20:35], v[88:91], v[84:87], v[20:35]
	s_waitcnt lgkmcnt(0)
	v_mfma_f32_32x32x16_bf16 v[36:51], v[92:95], v[80:83], v[36:51]
	v_mfma_f32_32x32x16_bf16 v[4:19], v[92:95], v[84:87], v[4:19]
	s_nop 7
	s_nop 7
